# GEMM K loops: the adjacent s_setprio 0 / s_setprio 1 flip pairs between MFMA sub-blocks removed (A/B of the per-segment flips)
# baseline (speedup 1.0000x reference)
; #define PG8_STAGE(bufoff, gbase, voff) do { _Pragma("unroll") for (int _i = 0; _i < 2; ++_i) \
;         __builtin_amdgcn_global_load_lds((const unsigned*)((const char*)(gbase) + (voff)[_i]), (PG8_LAS unsigned*)(lds + (bufoff) + ldsw + _i * 8192), 16, 0, 0); } while (0)
; #define PG8_LDA(dst, b, h) do { _Pragma("unroll") for (int m = 0; m < 4; ++m) _Pragma("unroll") for (int k = 0; k < 2; ++k) dst[m][k] = *(const PG8_LAS bf16x8*)(lds + PG8_SA(b, h) + aoff + m * 2048 + k * 1024); } while (0)
; #define PG8_LDB(dst, b, h) do { _Pragma("unroll") for (int n = 0; n < 2; ++n) _Pragma("unroll") for (int k = 0; k < 2; ++k) dst[n][k] = *(const PG8_LAS bf16x8*)(lds + PG8_SB(b, h) + boff + n * 2048 + k * 1024); } while (0)
; #define PG8_MMA(ai, bj, At, Bt) do { __builtin_amdgcn_s_setprio(1); _Pragma("unroll") for (int m = 0; m < 4; ++m) _Pragma("unroll") for (int n = 0; n < 2; ++n) _Pragma("unroll") for (int k = 0; k < 2; ++k) \
;         acc[ai][bj][m][n] = __builtin_amdgcn_mfma_f32_16x16x32_bf16(Bt[n][k], At[m][k], acc[ai][bj][m][n], 0, 0, 0); __builtin_amdgcn_s_setprio(0); } while (0)
; #define PG8_WAIT_V(n) asm volatile("s_waitcnt vmcnt(" #n ")" ::: "memory")
; #define PG8_WAIT_L(n) asm volatile("s_waitcnt lgkmcnt(" #n ")" ::: "memory")
; #define PG8_BAR __builtin_amdgcn_s_barrier()
; #define PG8_SCHED __builtin_amdgcn_sched_barrier(0)
; template <class Epi, class Sched, bool ALIGN_EPI = false, bool SP2 = false>
; __device__ __forceinline__ void gemm_phase(PG8_LAS unsigned char* lds, const Gemm g, const Sched S, const Epi E) {
;     ...
;             PG8_LDB(B0, 0, 0); PG8_LDB(B1, 0, 1); PG8_SCHED; PG8_LDA(At, 0, 0); PG8_STAGE(PG8_SA(1, 1), a1 + hstep, voffA);
;             PG8_WAIT_V(8); PG8_WAIT_L(0); PG8_BAR; PG8_MMA(0, 0, At, B0); PG8_MMA(0, 1, At, B1); PG8_BAR; PG8_SCHED;
;             PG8_LDA(At, 0, 1); PG8_STAGE(PG8_SB(0, 0), b2, voffB); PG8_STAGE(PG8_SB(0, 1), b2 + hstep, voffB); PG8_STAGE(PG8_SA(0, 0), a2, voffA);
;             PG8_WAIT_V(8); PG8_WAIT_L(0); PG8_BAR; PG8_MMA(1, 0, At, B0); PG8_MMA(1, 1, At, B1); PG8_BAR; PG8_SCHED;
.LBB0_180:
	v_add_u32_e32 v140, 0x10000, v143
	ds_read_b128 v[154:157], v140
	ds_read_b128 v[158:161], v140 offset:1024
	ds_read_b128 v[162:165], v140 offset:2048
	ds_read_b128 v[166:169], v140 offset:3072
	v_add_u32_e32 v140, 0x14000, v143
	ds_read_b128 v[170:173], v140
	ds_read_b128 v[174:177], v140 offset:1024
	ds_read_b128 v[182:185], v140 offset:2048
	ds_read_b128 v[198:201], v140 offset:3072
	s_add_i32 s20, s18, 2
	s_add_u32 s21, s16, 0x80
	s_addc_u32 s19, s17, 0
	s_add_i32 s25, 0, 0x10000
	s_cmp_eq_u32 s75, s18
	s_cselect_b32 s19, s1, s19
	s_cselect_b32 s18, s0, s21
	s_cselect_b32 s23, s59, s15
	s_cselect_b32 s22, s58, s14
	s_add_i32 s21, 0, 0x14000
	v_lshl_add_u64 v[140:141], s[16:17], 0, v[136:137]
	s_add_i32 m0, s68, 0xc000
	ds_read_b128 v[202:205], v146
	ds_read_b128 v[206:209], v146 offset:1024
	ds_read_b128 v[210:213], v146 offset:2048
	ds_read_b128 v[214:217], v146 offset:3072
	ds_read_b128 v[218:221], v146 offset:4096
	ds_read_b128 v[222:225], v146 offset:5120
	ds_read_b128 v[226:229], v146 offset:6144
	ds_read_b128 v[230:233], v146 offset:7168
	global_load_lds_dwordx4 v[140:141], off
	v_lshl_add_u64 v[140:141], s[16:17], 0, v[138:139]
	s_add_i32 m0, s68, 0xe000
	s_nop 0
	global_load_lds_dwordx4 v[140:141], off
	s_waitcnt vmcnt(8) lgkmcnt(0)
	s_barrier
	s_setprio 1
	v_mfma_f32_16x16x32_bf16 v[126:129], v[154:157], v[202:205], v[126:129]
	v_mfma_f32_16x16x32_bf16 v[118:121], v[162:165], v[202:205], v[118:121]
	v_mfma_f32_16x16x32_bf16 v[110:113], v[154:157], v[210:213], v[110:113]
	v_mfma_f32_16x16x32_bf16 v[102:105], v[162:165], v[210:213], v[102:105]
	v_mfma_f32_16x16x32_bf16 v[94:97], v[154:157], v[218:221], v[94:97]
	v_mfma_f32_16x16x32_bf16 v[86:89], v[162:165], v[218:221], v[86:89]
	v_mfma_f32_16x16x32_bf16 v[78:81], v[154:157], v[226:229], v[78:81]
	v_mfma_f32_16x16x32_bf16 v[70:73], v[162:165], v[226:229], v[70:73]
	v_mfma_f32_16x16x32_bf16 v[126:129], v[158:161], v[206:209], v[126:129]
	v_mfma_f32_16x16x32_bf16 v[118:121], v[166:169], v[206:209], v[118:121]
	v_mfma_f32_16x16x32_bf16 v[110:113], v[158:161], v[214:217], v[110:113]
	v_mfma_f32_16x16x32_bf16 v[102:105], v[166:169], v[214:217], v[102:105]
	v_mfma_f32_16x16x32_bf16 v[94:97], v[158:161], v[222:225], v[94:97]
	v_mfma_f32_16x16x32_bf16 v[86:89], v[166:169], v[222:225], v[86:89]
	v_mfma_f32_16x16x32_bf16 v[78:81], v[158:161], v[230:233], v[78:81]
	v_mfma_f32_16x16x32_bf16 v[70:73], v[166:169], v[230:233], v[70:73]
	v_mfma_f32_16x16x32_bf16 v[122:125], v[170:173], v[202:205], v[122:125]
	v_mfma_f32_16x16x32_bf16 v[114:117], v[182:185], v[202:205], v[114:117]
	v_mfma_f32_16x16x32_bf16 v[106:109], v[170:173], v[210:213], v[106:109]
	v_mfma_f32_16x16x32_bf16 v[98:101], v[182:185], v[210:213], v[98:101]
	v_mfma_f32_16x16x32_bf16 v[90:93], v[170:173], v[218:221], v[90:93]
	v_mfma_f32_16x16x32_bf16 v[82:85], v[182:185], v[218:221], v[82:85]
	v_mfma_f32_16x16x32_bf16 v[74:77], v[170:173], v[226:229], v[74:77]
	v_mfma_f32_16x16x32_bf16 v[66:69], v[182:185], v[226:229], v[66:69]
	v_mfma_f32_16x16x32_bf16 v[122:125], v[174:177], v[206:209], v[122:125]
	v_mfma_f32_16x16x32_bf16 v[114:117], v[198:201], v[206:209], v[114:117]
	v_mfma_f32_16x16x32_bf16 v[106:109], v[174:177], v[214:217], v[106:109]
	v_mfma_f32_16x16x32_bf16 v[98:101], v[198:201], v[214:217], v[98:101]
	v_mfma_f32_16x16x32_bf16 v[90:93], v[174:177], v[222:225], v[90:93]
	v_mfma_f32_16x16x32_bf16 v[82:85], v[198:201], v[222:225], v[82:85]
	v_mfma_f32_16x16x32_bf16 v[74:77], v[174:177], v[230:233], v[74:77]
	v_mfma_f32_16x16x32_bf16 v[66:69], v[198:201], v[230:233], v[66:69]
	s_setprio 0
	s_barrier
	s_add_i32 s25, s25, s61
	v_lshl_add_u64 v[140:141], s[22:23], 0, v[0:1]
	s_mov_b32 m0, s25
	ds_read_b128 v[202:205], v146 offset:16384
	ds_read_b128 v[206:209], v146 offset:17408
	ds_read_b128 v[210:213], v146 offset:18432
	ds_read_b128 v[214:217], v146 offset:19456
	ds_read_b128 v[218:221], v146 offset:20480
	ds_read_b128 v[222:225], v146 offset:21504
	ds_read_b128 v[226:229], v146 offset:22528
	ds_read_b128 v[230:233], v146 offset:23552
	global_load_lds_dwordx4 v[140:141], off
	s_add_i32 m0, s25, 0x2000
	v_lshl_add_u64 v[234:235], s[22:23], 0, v[130:131]
	s_add_u32 s22, s22, s28
	s_addc_u32 s23, s23, 0
	s_add_i32 s21, s21, s61
	global_load_lds_dwordx4 v[234:235], off
	v_lshl_add_u64 v[236:237], s[22:23], 0, v[0:1]
	s_mov_b32 m0, s21
	v_lshl_add_u64 v[238:239], s[22:23], 0, v[130:131]
	global_load_lds_dwordx4 v[236:237], off
	s_add_i32 m0, s21, 0x2000
	v_lshl_add_u64 v[240:241], s[18:19], 0, v[134:135]
	global_load_lds_dwordx4 v[238:239], off
	s_mov_b32 m0, s68
	v_lshl_add_u64 v[242:243], s[18:19], 0, v[132:133]
	global_load_lds_dwordx4 v[240:241], off
	s_mov_b32 m0, s69
	s_nop 0
	global_load_lds_dwordx4 v[242:243], off
	s_waitcnt vmcnt(8) lgkmcnt(0)
	s_barrier
; #define PG8_STAGE(bufoff, gbase, voff) do { _Pragma("unroll") for (int _i = 0; _i < 2; ++_i) \
;         __builtin_amdgcn_global_load_lds((const unsigned*)((const char*)(gbase) + (voff)[_i]), (PG8_LAS unsigned*)(lds + (bufoff) + ldsw + _i * 8192), 16, 0, 0); } while (0)
; #define PG8_LDA(dst, b, h) do { _Pragma("unroll") for (int m = 0; m < 4; ++m) _Pragma("unroll") for (int k = 0; k < 2; ++k) dst[m][k] = *(const PG8_LAS bf16x8*)(lds + PG8_SA(b, h) + aoff + m * 2048 + k * 1024); } while (0)
; #define PG8_LDB(dst, b, h) do { _Pragma("unroll") for (int n = 0; n < 2; ++n) _Pragma("unroll") for (int k = 0; k < 2; ++k) dst[n][k] = *(const PG8_LAS bf16x8*)(lds + PG8_SB(b, h) + boff + n * 2048 + k * 1024); } while (0)
; #define PG8_MMA(ai, bj, At, Bt) do { __builtin_amdgcn_s_setprio(1); _Pragma("unroll") for (int m = 0; m < 4; ++m) _Pragma("unroll") for (int n = 0; n < 2; ++n) _Pragma("unroll") for (int k = 0; k < 2; ++k) \
;         acc[ai][bj][m][n] = __builtin_amdgcn_mfma_f32_16x16x32_bf16(Bt[n][k], At[m][k], acc[ai][bj][m][n], 0, 0, 0); __builtin_amdgcn_s_setprio(0); } while (0)
; #define PG8_WAIT_V(n) asm volatile("s_waitcnt vmcnt(" #n ")" ::: "memory")
; #define PG8_WAIT_L(n) asm volatile("s_waitcnt lgkmcnt(" #n ")" ::: "memory")
; #define PG8_BAR __builtin_amdgcn_s_barrier()
; #define PG8_SCHED __builtin_amdgcn_sched_barrier(0)
; template <class Epi, class Sched, bool ALIGN_EPI = false, bool SP2 = false>
; __device__ __forceinline__ void gemm_phase(PG8_LAS unsigned char* lds, const Gemm g, const Sched S, const Epi E) {
;     ...
;             PG8_WAIT_V(8); PG8_WAIT_L(0); PG8_BAR; PG8_MMA(1, 0, At, B0); PG8_MMA(1, 1, At, B1); PG8_BAR; PG8_SCHED;
;             PG8_LDB(B0, 1, 0); PG8_LDB(B1, 1, 1); PG8_SCHED; PG8_LDA(At, 1, 0); PG8_STAGE(PG8_SA(0, 1), a2 + hstep, voffA);
;             PG8_WAIT_V(8); PG8_WAIT_L(0); PG8_BAR; PG8_MMA(0, 0, At, B0); PG8_MMA(0, 1, At, B1); PG8_BAR; PG8_SCHED;
	s_setprio 1
	v_mfma_f32_16x16x32_bf16 v[62:65], v[154:157], v[202:205], v[62:65]
	v_mfma_f32_16x16x32_bf16 v[54:57], v[162:165], v[202:205], v[54:57]
	v_mfma_f32_16x16x32_bf16 v[46:49], v[154:157], v[210:213], v[46:49]
	v_mfma_f32_16x16x32_bf16 v[38:41], v[162:165], v[210:213], v[38:41]
	v_mfma_f32_16x16x32_bf16 v[30:33], v[154:157], v[218:221], v[30:33]
	v_mfma_f32_16x16x32_bf16 v[22:25], v[162:165], v[218:221], v[22:25]
	v_mfma_f32_16x16x32_bf16 v[14:17], v[154:157], v[226:229], v[14:17]
	v_mfma_f32_16x16x32_bf16 v[6:9], v[162:165], v[226:229], v[6:9]
	v_mfma_f32_16x16x32_bf16 v[62:65], v[158:161], v[206:209], v[62:65]
	v_mfma_f32_16x16x32_bf16 v[54:57], v[166:169], v[206:209], v[54:57]
	v_mfma_f32_16x16x32_bf16 v[46:49], v[158:161], v[214:217], v[46:49]
	v_mfma_f32_16x16x32_bf16 v[38:41], v[166:169], v[214:217], v[38:41]
	v_mfma_f32_16x16x32_bf16 v[30:33], v[158:161], v[222:225], v[30:33]
	v_mfma_f32_16x16x32_bf16 v[22:25], v[166:169], v[222:225], v[22:25]
	v_mfma_f32_16x16x32_bf16 v[14:17], v[158:161], v[230:233], v[14:17]
	v_mfma_f32_16x16x32_bf16 v[6:9], v[166:169], v[230:233], v[6:9]
	v_mfma_f32_16x16x32_bf16 v[58:61], v[170:173], v[202:205], v[58:61]
	v_mfma_f32_16x16x32_bf16 v[50:53], v[182:185], v[202:205], v[50:53]
	v_mfma_f32_16x16x32_bf16 v[42:45], v[170:173], v[210:213], v[42:45]
	v_mfma_f32_16x16x32_bf16 v[34:37], v[182:185], v[210:213], v[34:37]
	v_mfma_f32_16x16x32_bf16 v[26:29], v[170:173], v[218:221], v[26:29]
	v_mfma_f32_16x16x32_bf16 v[18:21], v[182:185], v[218:221], v[18:21]
	v_mfma_f32_16x16x32_bf16 v[10:13], v[170:173], v[226:229], v[10:13]
	v_mfma_f32_16x16x32_bf16 v[2:5], v[182:185], v[226:229], v[2:5]
	v_mfma_f32_16x16x32_bf16 v[58:61], v[174:177], v[206:209], v[58:61]
	v_mfma_f32_16x16x32_bf16 v[50:53], v[198:201], v[206:209], v[50:53]
	v_mfma_f32_16x16x32_bf16 v[42:45], v[174:177], v[214:217], v[42:45]
	v_mfma_f32_16x16x32_bf16 v[34:37], v[198:201], v[214:217], v[34:37]
	v_mfma_f32_16x16x32_bf16 v[26:29], v[174:177], v[222:225], v[26:29]
	v_mfma_f32_16x16x32_bf16 v[18:21], v[198:201], v[222:225], v[18:21]
	v_mfma_f32_16x16x32_bf16 v[10:13], v[174:177], v[230:233], v[10:13]
	v_mfma_f32_16x16x32_bf16 v[2:5], v[198:201], v[230:233], v[2:5]
	s_setprio 0
	s_barrier
	v_add_u32_e32 v166, 0x18000, v143
	v_add_u32_e32 v186, 0x1c000, v143
	ds_read_b128 v[154:157], v166
	ds_read_b128 v[158:161], v166 offset:1024
	ds_read_b128 v[162:165], v166 offset:2048
	ds_read_b128 v[166:169], v166 offset:3072
	ds_read_b128 v[170:173], v186
	ds_read_b128 v[174:177], v186 offset:1024
	ds_read_b128 v[182:185], v186 offset:2048
	ds_read_b128 v[198:201], v186 offset:3072
	s_add_i32 s21, 0, 0x18000
	s_add_i32 s22, 0, 0x1c000
	s_add_u32 s18, s18, s28
	s_addc_u32 s19, s19, 0
	s_mov_b32 m0, s70
	v_lshl_add_u64 v[244:245], s[18:19], 0, v[134:135]
	ds_read_b128 v[202:205], v146 offset:32768
	ds_read_b128 v[206:209], v146 offset:33792
	ds_read_b128 v[210:213], v146 offset:34816
	ds_read_b128 v[214:217], v146 offset:35840
	ds_read_b128 v[218:221], v146 offset:36864
	ds_read_b128 v[222:225], v146 offset:37888
	ds_read_b128 v[226:229], v146 offset:38912
	ds_read_b128 v[230:233], v146 offset:39936
	global_load_lds_dwordx4 v[244:245], off
	v_lshl_add_u64 v[244:245], s[18:19], 0, v[132:133]
	s_mov_b32 m0, s71
	s_nop 0
	global_load_lds_dwordx4 v[244:245], off
	s_waitcnt vmcnt(8) lgkmcnt(0)
	s_barrier
	s_setprio 1
	v_mfma_f32_16x16x32_bf16 v[126:129], v[154:157], v[202:205], v[126:129]
	v_mfma_f32_16x16x32_bf16 v[118:121], v[162:165], v[202:205], v[118:121]
	v_mfma_f32_16x16x32_bf16 v[110:113], v[154:157], v[210:213], v[110:113]
	v_mfma_f32_16x16x32_bf16 v[102:105], v[162:165], v[210:213], v[102:105]
	v_mfma_f32_16x16x32_bf16 v[94:97], v[154:157], v[218:221], v[94:97]
	v_mfma_f32_16x16x32_bf16 v[86:89], v[162:165], v[218:221], v[86:89]
	v_mfma_f32_16x16x32_bf16 v[78:81], v[154:157], v[226:229], v[78:81]
	v_mfma_f32_16x16x32_bf16 v[70:73], v[162:165], v[226:229], v[70:73]
	v_mfma_f32_16x16x32_bf16 v[126:129], v[158:161], v[206:209], v[126:129]
	v_mfma_f32_16x16x32_bf16 v[118:121], v[166:169], v[206:209], v[118:121]
	v_mfma_f32_16x16x32_bf16 v[110:113], v[158:161], v[214:217], v[110:113]
	v_mfma_f32_16x16x32_bf16 v[102:105], v[166:169], v[214:217], v[102:105]
	v_mfma_f32_16x16x32_bf16 v[94:97], v[158:161], v[222:225], v[94:97]
	v_mfma_f32_16x16x32_bf16 v[86:89], v[166:169], v[222:225], v[86:89]
	v_mfma_f32_16x16x32_bf16 v[78:81], v[158:161], v[230:233], v[78:81]
	v_mfma_f32_16x16x32_bf16 v[70:73], v[166:169], v[230:233], v[70:73]
	v_mfma_f32_16x16x32_bf16 v[122:125], v[170:173], v[202:205], v[122:125]
	v_mfma_f32_16x16x32_bf16 v[114:117], v[182:185], v[202:205], v[114:117]
	v_mfma_f32_16x16x32_bf16 v[106:109], v[170:173], v[210:213], v[106:109]
	v_mfma_f32_16x16x32_bf16 v[98:101], v[182:185], v[210:213], v[98:101]
	v_mfma_f32_16x16x32_bf16 v[90:93], v[170:173], v[218:221], v[90:93]
	v_mfma_f32_16x16x32_bf16 v[82:85], v[182:185], v[218:221], v[82:85]
	v_mfma_f32_16x16x32_bf16 v[74:77], v[170:173], v[226:229], v[74:77]
	v_mfma_f32_16x16x32_bf16 v[66:69], v[182:185], v[226:229], v[66:69]
	v_mfma_f32_16x16x32_bf16 v[122:125], v[174:177], v[206:209], v[122:125]
	v_mfma_f32_16x16x32_bf16 v[114:117], v[198:201], v[206:209], v[114:117]
	v_mfma_f32_16x16x32_bf16 v[106:109], v[174:177], v[214:217], v[106:109]
	v_mfma_f32_16x16x32_bf16 v[98:101], v[198:201], v[214:217], v[98:101]
	v_mfma_f32_16x16x32_bf16 v[90:93], v[174:177], v[222:225], v[90:93]
	v_mfma_f32_16x16x32_bf16 v[82:85], v[198:201], v[222:225], v[82:85]
	v_mfma_f32_16x16x32_bf16 v[74:77], v[174:177], v[230:233], v[74:77]
	v_mfma_f32_16x16x32_bf16 v[66:69], v[198:201], v[230:233], v[66:69]
	s_setprio 0
	s_barrier
; #define PG8_STAGE(bufoff, gbase, voff) do { _Pragma("unroll") for (int _i = 0; _i < 2; ++_i) \
;         __builtin_amdgcn_global_load_lds((const unsigned*)((const char*)(gbase) + (voff)[_i]), (PG8_LAS unsigned*)(lds + (bufoff) + ldsw + _i * 8192), 16, 0, 0); } while (0)
; #define PG8_LDA(dst, b, h) do { _Pragma("unroll") for (int m = 0; m < 4; ++m) _Pragma("unroll") for (int k = 0; k < 2; ++k) dst[m][k] = *(const PG8_LAS bf16x8*)(lds + PG8_SA(b, h) + aoff + m * 2048 + k * 1024); } while (0)
; #define PG8_MMA(ai, bj, At, Bt) do { __builtin_amdgcn_s_setprio(1); _Pragma("unroll") for (int m = 0; m < 4; ++m) _Pragma("unroll") for (int n = 0; n < 2; ++n) _Pragma("unroll") for (int k = 0; k < 2; ++k) \
;         acc[ai][bj][m][n] = __builtin_amdgcn_mfma_f32_16x16x32_bf16(Bt[n][k], At[m][k], acc[ai][bj][m][n], 0, 0, 0); __builtin_amdgcn_s_setprio(0); } while (0)
; #define PG8_WAIT_V(n) asm volatile("s_waitcnt vmcnt(" #n ")" ::: "memory")
; #define PG8_WAIT_L(n) asm volatile("s_waitcnt lgkmcnt(" #n ")" ::: "memory")
; #define PG8_BAR __builtin_amdgcn_s_barrier()
; #define PG8_SCHED __builtin_amdgcn_sched_barrier(0)
; template <class Epi, class Sched, bool ALIGN_EPI = false, bool SP2 = false>
; __device__ __forceinline__ void gemm_phase(PG8_LAS unsigned char* lds, const Gemm g, const Sched S, const Epi E) {
;     ...
;             PG8_LDA(At, 1, 1); PG8_STAGE(PG8_SB(1, 0), b3, voffB); PG8_STAGE(PG8_SB(1, 1), b3 + hstep, voffB); PG8_STAGE(PG8_SA(1, 0), a3, voffA);
;             PG8_WAIT_V(8); PG8_WAIT_L(0); PG8_BAR; PG8_MMA(1, 0, At, B0); PG8_MMA(1, 1, At, B1); PG8_BAR; PG8_SCHED;
	s_add_i32 s18, s21, s61
	v_lshl_add_u64 v[140:141], v[140:141], 0, s[12:13]
	s_mov_b32 m0, s18
	ds_read_b128 v[202:205], v146 offset:49152
	ds_read_b128 v[206:209], v146 offset:50176
	ds_read_b128 v[210:213], v146 offset:51200
	ds_read_b128 v[214:217], v146 offset:52224
	ds_read_b128 v[218:221], v146 offset:53248
	ds_read_b128 v[222:225], v146 offset:54272
	ds_read_b128 v[226:229], v146 offset:55296
	ds_read_b128 v[230:233], v146 offset:56320
	global_load_lds_dwordx4 v[140:141], off
	v_lshl_add_u64 v[140:141], v[234:235], 0, s[12:13]
	s_add_i32 m0, s18, 0x2000
	s_add_i32 s18, s22, s61
	global_load_lds_dwordx4 v[140:141], off
	v_lshl_add_u64 v[140:141], v[236:237], 0, s[12:13]
	s_mov_b32 m0, s18
	s_nop 0
	global_load_lds_dwordx4 v[140:141], off
	v_lshl_add_u64 v[140:141], v[238:239], 0, s[12:13]
	s_add_i32 m0, s18, 0x2000
	s_nop 0
	global_load_lds_dwordx4 v[140:141], off
	v_lshl_add_u64 v[140:141], v[240:241], 0, s[12:13]
	s_mov_b32 m0, s73
	s_nop 0
	global_load_lds_dwordx4 v[140:141], off
	v_lshl_add_u64 v[140:141], v[242:243], 0, s[12:13]
	s_mov_b32 m0, s74
	s_nop 0
	global_load_lds_dwordx4 v[140:141], off
	s_waitcnt vmcnt(8) lgkmcnt(0)
	s_barrier
	s_setprio 1
	v_mfma_f32_16x16x32_bf16 v[62:65], v[154:157], v[202:205], v[62:65]
	v_mfma_f32_16x16x32_bf16 v[54:57], v[162:165], v[202:205], v[54:57]
	v_mfma_f32_16x16x32_bf16 v[46:49], v[154:157], v[210:213], v[46:49]
	v_mfma_f32_16x16x32_bf16 v[38:41], v[162:165], v[210:213], v[38:41]
	v_mfma_f32_16x16x32_bf16 v[30:33], v[154:157], v[218:221], v[30:33]
	v_mfma_f32_16x16x32_bf16 v[22:25], v[162:165], v[218:221], v[22:25]
	v_mfma_f32_16x16x32_bf16 v[14:17], v[154:157], v[226:229], v[14:17]
	v_mfma_f32_16x16x32_bf16 v[6:9], v[162:165], v[226:229], v[6:9]
	v_mfma_f32_16x16x32_bf16 v[62:65], v[158:161], v[206:209], v[62:65]
	v_mfma_f32_16x16x32_bf16 v[54:57], v[166:169], v[206:209], v[54:57]
	v_mfma_f32_16x16x32_bf16 v[46:49], v[158:161], v[214:217], v[46:49]
	v_mfma_f32_16x16x32_bf16 v[38:41], v[166:169], v[214:217], v[38:41]
	v_mfma_f32_16x16x32_bf16 v[30:33], v[158:161], v[222:225], v[30:33]
	v_mfma_f32_16x16x32_bf16 v[22:25], v[166:169], v[222:225], v[22:25]
	v_mfma_f32_16x16x32_bf16 v[14:17], v[158:161], v[230:233], v[14:17]
	v_mfma_f32_16x16x32_bf16 v[6:9], v[166:169], v[230:233], v[6:9]
	v_mfma_f32_16x16x32_bf16 v[58:61], v[170:173], v[202:205], v[58:61]
	v_mfma_f32_16x16x32_bf16 v[50:53], v[182:185], v[202:205], v[50:53]
	v_mfma_f32_16x16x32_bf16 v[42:45], v[170:173], v[210:213], v[42:45]
	v_mfma_f32_16x16x32_bf16 v[34:37], v[182:185], v[210:213], v[34:37]
	v_mfma_f32_16x16x32_bf16 v[26:29], v[170:173], v[218:221], v[26:29]
	v_mfma_f32_16x16x32_bf16 v[18:21], v[182:185], v[218:221], v[18:21]
	v_mfma_f32_16x16x32_bf16 v[10:13], v[170:173], v[226:229], v[10:13]
	v_mfma_f32_16x16x32_bf16 v[2:5], v[182:185], v[226:229], v[2:5]
	v_mfma_f32_16x16x32_bf16 v[58:61], v[174:177], v[206:209], v[58:61]
	v_mfma_f32_16x16x32_bf16 v[50:53], v[198:201], v[206:209], v[50:53]
	v_mfma_f32_16x16x32_bf16 v[42:45], v[174:177], v[214:217], v[42:45]
	v_mfma_f32_16x16x32_bf16 v[34:37], v[198:201], v[214:217], v[34:37]
	v_mfma_f32_16x16x32_bf16 v[26:29], v[174:177], v[222:225], v[26:29]
	v_mfma_f32_16x16x32_bf16 v[18:21], v[198:201], v[222:225], v[18:21]
	v_mfma_f32_16x16x32_bf16 v[10:13], v[174:177], v[230:233], v[10:13]
	v_mfma_f32_16x16x32_bf16 v[2:5], v[198:201], v[230:233], v[2:5]
	s_setprio 0
	s_add_u32 s16, s16, 0x100
	s_addc_u32 s17, s17, 0
	s_add_u32 s14, s14, 0x100
	s_addc_u32 s15, s15, 0
	s_cmp_ge_u32 s20, s72
	s_mov_b32 s18, s20
	s_barrier
	s_cbranch_scc0 .LBB0_180
	s_and_b64 vcc, exec, s[56:57]
	s_cbranch_vccz .LBB0_183
	s_barrier

; #define PG8_STAGE(bufoff, gbase, voff) do { _Pragma("unroll") for (int _i = 0; _i < 2; ++_i) \
;         __builtin_amdgcn_global_load_lds((const unsigned*)((const char*)(gbase) + (voff)[_i]), (PG8_LAS unsigned*)(lds + (bufoff) + ldsw + _i * 8192), 16, 0, 0); } while (0)
; #define PG8_LDA(dst, b, h) do { _Pragma("unroll") for (int m = 0; m < 4; ++m) _Pragma("unroll") for (int k = 0; k < 2; ++k) dst[m][k] = *(const PG8_LAS bf16x8*)(lds + PG8_SA(b, h) + aoff + m * 2048 + k * 1024); } while (0)
; #define PG8_LDB(dst, b, h) do { _Pragma("unroll") for (int n = 0; n < 2; ++n) _Pragma("unroll") for (int k = 0; k < 2; ++k) dst[n][k] = *(const PG8_LAS bf16x8*)(lds + PG8_SB(b, h) + boff + n * 2048 + k * 1024); } while (0)
; #define PG8_MMA(ai, bj, At, Bt) do { __builtin_amdgcn_s_setprio(1); _Pragma("unroll") for (int m = 0; m < 4; ++m) _Pragma("unroll") for (int n = 0; n < 2; ++n) _Pragma("unroll") for (int k = 0; k < 2; ++k) \
;         acc[ai][bj][m][n] = __builtin_amdgcn_mfma_f32_16x16x32_bf16(Bt[n][k], At[m][k], acc[ai][bj][m][n], 0, 0, 0); __builtin_amdgcn_s_setprio(0); } while (0)
; #define PG8_WAIT_V(n) asm volatile("s_waitcnt vmcnt(" #n ")" ::: "memory")
; #define PG8_WAIT_L(n) asm volatile("s_waitcnt lgkmcnt(" #n ")" ::: "memory")
; #define PG8_BAR __builtin_amdgcn_s_barrier()
; #define PG8_SCHED __builtin_amdgcn_sched_barrier(0)
; template <class Epi, class Sched, bool ALIGN_EPI = false, bool SP2 = false>
; __device__ __forceinline__ void gemm_phase(PG8_LAS unsigned char* lds, const Gemm g, const Sched S, const Epi E) {
;     ...
;             PG8_LDB(B0, 0, 0); PG8_LDB(B1, 0, 1); PG8_SCHED; PG8_LDA(At, 0, 0); PG8_STAGE(PG8_SA(1, 1), a1 + hstep, voffA);
;             PG8_WAIT_V(8); PG8_WAIT_L(0); PG8_BAR; PG8_MMA(0, 0, At, B0); PG8_MMA(0, 1, At, B1); PG8_BAR; PG8_SCHED;
;             PG8_LDA(At, 0, 1); PG8_STAGE(PG8_SB(0, 0), b2, voffB); PG8_STAGE(PG8_SB(0, 1), b2 + hstep, voffB); PG8_STAGE(PG8_SA(0, 0), a2, voffA);
;             PG8_WAIT_V(8); PG8_WAIT_L(0); PG8_BAR; PG8_MMA(1, 0, At, B0); PG8_MMA(1, 1, At, B1); PG8_BAR; PG8_SCHED;
.LBB0_224:
	v_add_u32_e32 v141, 0x10000, v147
	ds_read_b128 v[154:157], v141
	ds_read_b128 v[158:161], v141 offset:1024
	ds_read_b128 v[162:165], v141 offset:2048
	ds_read_b128 v[166:169], v141 offset:3072
	v_add_u32_e32 v141, 0x14000, v147
	ds_read_b128 v[170:173], v141
	ds_read_b128 v[174:177], v141 offset:1024
	ds_read_b128 v[182:185], v141 offset:2048
	ds_read_b128 v[198:201], v141 offset:3072
	s_add_i32 s21, s20, 2
	s_add_u32 s22, s30, 0x80
	s_addc_u32 s23, s31, 0
	s_add_i32 s26, 0, 0x10000
	s_cmp_eq_u32 s81, s20
	s_cselect_b32 s75, s1, s23
	s_cselect_b32 s74, s0, s22
	s_cselect_b32 s23, s19, s15
	s_cselect_b32 s22, s18, s14
	s_add_i32 s20, 0, 0x14000
	v_lshl_add_u64 v[234:235], s[30:31], 0, v[136:137]
	s_add_i32 m0, s85, 0xc000
	ds_read_b128 v[202:205], v152
	ds_read_b128 v[206:209], v152 offset:1024
	ds_read_b128 v[210:213], v152 offset:2048
	ds_read_b128 v[214:217], v152 offset:3072
	ds_read_b128 v[218:221], v152 offset:4096
	ds_read_b128 v[222:225], v152 offset:5120
	ds_read_b128 v[226:229], v152 offset:6144
	ds_read_b128 v[230:233], v152 offset:7168
	global_load_lds_dwordx4 v[234:235], off
	v_lshl_add_u64 v[234:235], s[30:31], 0, v[138:139]
	s_add_i32 m0, s85, 0xe000
	s_nop 0
	global_load_lds_dwordx4 v[234:235], off
	s_waitcnt vmcnt(8) lgkmcnt(0)
	s_barrier
	s_setprio 1
	v_mfma_f32_16x16x32_bf16 v[126:129], v[154:157], v[202:205], v[126:129]
	v_mfma_f32_16x16x32_bf16 v[122:125], v[162:165], v[202:205], v[122:125]
	v_mfma_f32_16x16x32_bf16 v[110:113], v[154:157], v[210:213], v[110:113]
	v_mfma_f32_16x16x32_bf16 v[106:109], v[162:165], v[210:213], v[106:109]
	v_mfma_f32_16x16x32_bf16 v[94:97], v[154:157], v[218:221], v[94:97]
	v_mfma_f32_16x16x32_bf16 v[90:93], v[162:165], v[218:221], v[90:93]
	v_mfma_f32_16x16x32_bf16 v[78:81], v[154:157], v[226:229], v[78:81]
	v_mfma_f32_16x16x32_bf16 v[74:77], v[162:165], v[226:229], v[74:77]
	v_mfma_f32_16x16x32_bf16 v[126:129], v[158:161], v[206:209], v[126:129]
	v_mfma_f32_16x16x32_bf16 v[122:125], v[166:169], v[206:209], v[122:125]
	v_mfma_f32_16x16x32_bf16 v[110:113], v[158:161], v[214:217], v[110:113]
	v_mfma_f32_16x16x32_bf16 v[106:109], v[166:169], v[214:217], v[106:109]
	v_mfma_f32_16x16x32_bf16 v[94:97], v[158:161], v[222:225], v[94:97]
	v_mfma_f32_16x16x32_bf16 v[90:93], v[166:169], v[222:225], v[90:93]
	v_mfma_f32_16x16x32_bf16 v[78:81], v[158:161], v[230:233], v[78:81]
	v_mfma_f32_16x16x32_bf16 v[74:77], v[166:169], v[230:233], v[74:77]
	v_mfma_f32_16x16x32_bf16 v[118:121], v[170:173], v[202:205], v[118:121]
	v_mfma_f32_16x16x32_bf16 v[114:117], v[182:185], v[202:205], v[114:117]
	v_mfma_f32_16x16x32_bf16 v[102:105], v[170:173], v[210:213], v[102:105]
	v_mfma_f32_16x16x32_bf16 v[98:101], v[182:185], v[210:213], v[98:101]
	v_mfma_f32_16x16x32_bf16 v[86:89], v[170:173], v[218:221], v[86:89]
	v_mfma_f32_16x16x32_bf16 v[82:85], v[182:185], v[218:221], v[82:85]
	v_mfma_f32_16x16x32_bf16 v[70:73], v[170:173], v[226:229], v[70:73]
	v_mfma_f32_16x16x32_bf16 v[66:69], v[182:185], v[226:229], v[66:69]
	v_mfma_f32_16x16x32_bf16 v[118:121], v[174:177], v[206:209], v[118:121]
	v_mfma_f32_16x16x32_bf16 v[114:117], v[198:201], v[206:209], v[114:117]
	v_mfma_f32_16x16x32_bf16 v[102:105], v[174:177], v[214:217], v[102:105]
	v_mfma_f32_16x16x32_bf16 v[98:101], v[198:201], v[214:217], v[98:101]
	v_mfma_f32_16x16x32_bf16 v[86:89], v[174:177], v[222:225], v[86:89]
	v_mfma_f32_16x16x32_bf16 v[82:85], v[198:201], v[222:225], v[82:85]
	v_mfma_f32_16x16x32_bf16 v[70:73], v[174:177], v[230:233], v[70:73]
	v_mfma_f32_16x16x32_bf16 v[66:69], v[198:201], v[230:233], v[66:69]
	s_setprio 0
	s_barrier
	s_add_i32 s26, s26, s84
	v_lshl_add_u64 v[234:235], s[22:23], 0, v[0:1]
	s_mov_b32 m0, s26
	ds_read_b128 v[202:205], v152 offset:16384
	ds_read_b128 v[206:209], v152 offset:17408
	ds_read_b128 v[210:213], v152 offset:18432
	ds_read_b128 v[214:217], v152 offset:19456
	ds_read_b128 v[218:221], v152 offset:20480
	ds_read_b128 v[222:225], v152 offset:21504
	ds_read_b128 v[226:229], v152 offset:22528
	ds_read_b128 v[230:233], v152 offset:23552
	global_load_lds_dwordx4 v[234:235], off
	s_add_i32 m0, s26, 0x2000
	v_lshl_add_u64 v[236:237], s[22:23], 0, v[134:135]
	s_add_u32 s22, s22, s52
	s_addc_u32 s23, s23, 0
	s_add_i32 s20, s20, s84
	global_load_lds_dwordx4 v[236:237], off
	v_lshl_add_u64 v[238:239], s[22:23], 0, v[0:1]
	s_mov_b32 m0, s20
	v_lshl_add_u64 v[240:241], s[22:23], 0, v[134:135]
	global_load_lds_dwordx4 v[238:239], off
	s_add_i32 m0, s20, 0x2000
	v_lshl_add_u64 v[242:243], s[74:75], 0, v[130:131]
	global_load_lds_dwordx4 v[240:241], off
	s_mov_b32 m0, s85
	v_lshl_add_u64 v[244:245], s[74:75], 0, v[132:133]
	global_load_lds_dwordx4 v[242:243], off
	s_mov_b32 m0, s86
	s_nop 0
	global_load_lds_dwordx4 v[244:245], off
	s_waitcnt vmcnt(8) lgkmcnt(0)
	s_barrier
; #define PG8_STAGE(bufoff, gbase, voff) do { _Pragma("unroll") for (int _i = 0; _i < 2; ++_i) \
;         __builtin_amdgcn_global_load_lds((const unsigned*)((const char*)(gbase) + (voff)[_i]), (PG8_LAS unsigned*)(lds + (bufoff) + ldsw + _i * 8192), 16, 0, 0); } while (0)
; #define PG8_LDA(dst, b, h) do { _Pragma("unroll") for (int m = 0; m < 4; ++m) _Pragma("unroll") for (int k = 0; k < 2; ++k) dst[m][k] = *(const PG8_LAS bf16x8*)(lds + PG8_SA(b, h) + aoff + m * 2048 + k * 1024); } while (0)
; #define PG8_LDB(dst, b, h) do { _Pragma("unroll") for (int n = 0; n < 2; ++n) _Pragma("unroll") for (int k = 0; k < 2; ++k) dst[n][k] = *(const PG8_LAS bf16x8*)(lds + PG8_SB(b, h) + boff + n * 2048 + k * 1024); } while (0)
; #define PG8_MMA(ai, bj, At, Bt) do { __builtin_amdgcn_s_setprio(1); _Pragma("unroll") for (int m = 0; m < 4; ++m) _Pragma("unroll") for (int n = 0; n < 2; ++n) _Pragma("unroll") for (int k = 0; k < 2; ++k) \
;         acc[ai][bj][m][n] = __builtin_amdgcn_mfma_f32_16x16x32_bf16(Bt[n][k], At[m][k], acc[ai][bj][m][n], 0, 0, 0); __builtin_amdgcn_s_setprio(0); } while (0)
; #define PG8_WAIT_V(n) asm volatile("s_waitcnt vmcnt(" #n ")" ::: "memory")
; #define PG8_WAIT_L(n) asm volatile("s_waitcnt lgkmcnt(" #n ")" ::: "memory")
; #define PG8_BAR __builtin_amdgcn_s_barrier()
; #define PG8_SCHED __builtin_amdgcn_sched_barrier(0)
; template <class Epi, class Sched, bool ALIGN_EPI = false, bool SP2 = false>
; __device__ __forceinline__ void gemm_phase(PG8_LAS unsigned char* lds, const Gemm g, const Sched S, const Epi E) {
;     ...
;             PG8_WAIT_V(8); PG8_WAIT_L(0); PG8_BAR; PG8_MMA(1, 0, At, B0); PG8_MMA(1, 1, At, B1); PG8_BAR; PG8_SCHED;
;             PG8_LDB(B0, 1, 0); PG8_LDB(B1, 1, 1); PG8_SCHED; PG8_LDA(At, 1, 0); PG8_STAGE(PG8_SA(0, 1), a2 + hstep, voffA);
;             PG8_WAIT_V(8); PG8_WAIT_L(0); PG8_BAR; PG8_MMA(0, 0, At, B0); PG8_MMA(0, 1, At, B1); PG8_BAR; PG8_SCHED;
	s_setprio 1
	v_mfma_f32_16x16x32_bf16 v[62:65], v[154:157], v[202:205], v[62:65]
	v_mfma_f32_16x16x32_bf16 v[58:61], v[162:165], v[202:205], v[58:61]
	v_mfma_f32_16x16x32_bf16 v[46:49], v[154:157], v[210:213], v[46:49]
	v_mfma_f32_16x16x32_bf16 v[42:45], v[162:165], v[210:213], v[42:45]
	v_mfma_f32_16x16x32_bf16 v[30:33], v[154:157], v[218:221], v[30:33]
	v_mfma_f32_16x16x32_bf16 v[26:29], v[162:165], v[218:221], v[26:29]
	v_mfma_f32_16x16x32_bf16 v[14:17], v[154:157], v[226:229], v[14:17]
	v_mfma_f32_16x16x32_bf16 v[10:13], v[162:165], v[226:229], v[10:13]
	v_mfma_f32_16x16x32_bf16 v[62:65], v[158:161], v[206:209], v[62:65]
	v_mfma_f32_16x16x32_bf16 v[58:61], v[166:169], v[206:209], v[58:61]
	v_mfma_f32_16x16x32_bf16 v[46:49], v[158:161], v[214:217], v[46:49]
	v_mfma_f32_16x16x32_bf16 v[42:45], v[166:169], v[214:217], v[42:45]
	v_mfma_f32_16x16x32_bf16 v[30:33], v[158:161], v[222:225], v[30:33]
	v_mfma_f32_16x16x32_bf16 v[26:29], v[166:169], v[222:225], v[26:29]
	v_mfma_f32_16x16x32_bf16 v[14:17], v[158:161], v[230:233], v[14:17]
	v_mfma_f32_16x16x32_bf16 v[10:13], v[166:169], v[230:233], v[10:13]
	v_mfma_f32_16x16x32_bf16 v[54:57], v[170:173], v[202:205], v[54:57]
	v_mfma_f32_16x16x32_bf16 v[50:53], v[182:185], v[202:205], v[50:53]
	v_mfma_f32_16x16x32_bf16 v[38:41], v[170:173], v[210:213], v[38:41]
	v_mfma_f32_16x16x32_bf16 v[34:37], v[182:185], v[210:213], v[34:37]
	v_mfma_f32_16x16x32_bf16 v[22:25], v[170:173], v[218:221], v[22:25]
	v_mfma_f32_16x16x32_bf16 v[18:21], v[182:185], v[218:221], v[18:21]
	v_mfma_f32_16x16x32_bf16 v[6:9], v[170:173], v[226:229], v[6:9]
	v_mfma_f32_16x16x32_bf16 v[2:5], v[182:185], v[226:229], v[2:5]
	v_mfma_f32_16x16x32_bf16 v[54:57], v[174:177], v[206:209], v[54:57]
	v_mfma_f32_16x16x32_bf16 v[50:53], v[198:201], v[206:209], v[50:53]
	v_mfma_f32_16x16x32_bf16 v[38:41], v[174:177], v[214:217], v[38:41]
	v_mfma_f32_16x16x32_bf16 v[34:37], v[198:201], v[214:217], v[34:37]
	v_mfma_f32_16x16x32_bf16 v[22:25], v[174:177], v[222:225], v[22:25]
	v_mfma_f32_16x16x32_bf16 v[18:21], v[198:201], v[222:225], v[18:21]
	v_mfma_f32_16x16x32_bf16 v[6:9], v[174:177], v[230:233], v[6:9]
	v_mfma_f32_16x16x32_bf16 v[2:5], v[198:201], v[230:233], v[2:5]
	s_setprio 0
	s_barrier
	v_add_u32_e32 v141, 0x18000, v147
	ds_read_b128 v[154:157], v141
	ds_read_b128 v[158:161], v141 offset:1024
	ds_read_b128 v[162:165], v141 offset:2048
	ds_read_b128 v[166:169], v141 offset:3072
	v_add_u32_e32 v141, 0x1c000, v147
	ds_read_b128 v[170:173], v141
	ds_read_b128 v[174:177], v141 offset:1024
	ds_read_b128 v[182:185], v141 offset:2048
	ds_read_b128 v[198:201], v141 offset:3072
	s_add_i32 s20, 0, 0x18000
	s_add_i32 s26, 0, 0x1c000
	s_add_u32 s22, s74, s52
	s_addc_u32 s23, s75, 0
	s_mov_b32 m0, s87
	v_lshl_add_u64 v[246:247], s[22:23], 0, v[130:131]
	ds_read_b128 v[202:205], v152 offset:32768
	ds_read_b128 v[206:209], v152 offset:33792
	ds_read_b128 v[210:213], v152 offset:34816
	ds_read_b128 v[214:217], v152 offset:35840
	ds_read_b128 v[218:221], v152 offset:36864
	ds_read_b128 v[222:225], v152 offset:37888
	ds_read_b128 v[226:229], v152 offset:38912
	ds_read_b128 v[230:233], v152 offset:39936
	global_load_lds_dwordx4 v[246:247], off
	v_lshl_add_u64 v[246:247], s[22:23], 0, v[132:133]
	s_mov_b32 m0, s88
	s_nop 0
	global_load_lds_dwordx4 v[246:247], off
	s_waitcnt vmcnt(8) lgkmcnt(0)
	s_barrier
	s_setprio 1
	v_mfma_f32_16x16x32_bf16 v[126:129], v[154:157], v[202:205], v[126:129]
	v_mfma_f32_16x16x32_bf16 v[122:125], v[162:165], v[202:205], v[122:125]
	v_mfma_f32_16x16x32_bf16 v[110:113], v[154:157], v[210:213], v[110:113]
	v_mfma_f32_16x16x32_bf16 v[106:109], v[162:165], v[210:213], v[106:109]
	v_mfma_f32_16x16x32_bf16 v[94:97], v[154:157], v[218:221], v[94:97]
	v_mfma_f32_16x16x32_bf16 v[90:93], v[162:165], v[218:221], v[90:93]
	v_mfma_f32_16x16x32_bf16 v[78:81], v[154:157], v[226:229], v[78:81]
	v_mfma_f32_16x16x32_bf16 v[74:77], v[162:165], v[226:229], v[74:77]
	v_mfma_f32_16x16x32_bf16 v[126:129], v[158:161], v[206:209], v[126:129]
	v_mfma_f32_16x16x32_bf16 v[122:125], v[166:169], v[206:209], v[122:125]
	v_mfma_f32_16x16x32_bf16 v[110:113], v[158:161], v[214:217], v[110:113]
	v_mfma_f32_16x16x32_bf16 v[106:109], v[166:169], v[214:217], v[106:109]
	v_mfma_f32_16x16x32_bf16 v[94:97], v[158:161], v[222:225], v[94:97]
	v_mfma_f32_16x16x32_bf16 v[90:93], v[166:169], v[222:225], v[90:93]
	v_mfma_f32_16x16x32_bf16 v[78:81], v[158:161], v[230:233], v[78:81]
	v_mfma_f32_16x16x32_bf16 v[74:77], v[166:169], v[230:233], v[74:77]
	v_mfma_f32_16x16x32_bf16 v[118:121], v[170:173], v[202:205], v[118:121]
	v_mfma_f32_16x16x32_bf16 v[114:117], v[182:185], v[202:205], v[114:117]
	v_mfma_f32_16x16x32_bf16 v[102:105], v[170:173], v[210:213], v[102:105]
	v_mfma_f32_16x16x32_bf16 v[98:101], v[182:185], v[210:213], v[98:101]
	v_mfma_f32_16x16x32_bf16 v[86:89], v[170:173], v[218:221], v[86:89]
	v_mfma_f32_16x16x32_bf16 v[82:85], v[182:185], v[218:221], v[82:85]
	v_mfma_f32_16x16x32_bf16 v[70:73], v[170:173], v[226:229], v[70:73]
	v_mfma_f32_16x16x32_bf16 v[66:69], v[182:185], v[226:229], v[66:69]
	v_mfma_f32_16x16x32_bf16 v[118:121], v[174:177], v[206:209], v[118:121]
	v_mfma_f32_16x16x32_bf16 v[114:117], v[198:201], v[206:209], v[114:117]
	v_mfma_f32_16x16x32_bf16 v[102:105], v[174:177], v[214:217], v[102:105]
	v_mfma_f32_16x16x32_bf16 v[98:101], v[198:201], v[214:217], v[98:101]
	v_mfma_f32_16x16x32_bf16 v[86:89], v[174:177], v[222:225], v[86:89]
	v_mfma_f32_16x16x32_bf16 v[82:85], v[198:201], v[222:225], v[82:85]
	v_mfma_f32_16x16x32_bf16 v[70:73], v[174:177], v[230:233], v[70:73]
	v_mfma_f32_16x16x32_bf16 v[66:69], v[198:201], v[230:233], v[66:69]
	s_setprio 0
	s_barrier
; #define PG8_STAGE(bufoff, gbase, voff) do { _Pragma("unroll") for (int _i = 0; _i < 2; ++_i) \
;         __builtin_amdgcn_global_load_lds((const unsigned*)((const char*)(gbase) + (voff)[_i]), (PG8_LAS unsigned*)(lds + (bufoff) + ldsw + _i * 8192), 16, 0, 0); } while (0)
; #define PG8_LDA(dst, b, h) do { _Pragma("unroll") for (int m = 0; m < 4; ++m) _Pragma("unroll") for (int k = 0; k < 2; ++k) dst[m][k] = *(const PG8_LAS bf16x8*)(lds + PG8_SA(b, h) + aoff + m * 2048 + k * 1024); } while (0)
; #define PG8_MMA(ai, bj, At, Bt) do { __builtin_amdgcn_s_setprio(1); _Pragma("unroll") for (int m = 0; m < 4; ++m) _Pragma("unroll") for (int n = 0; n < 2; ++n) _Pragma("unroll") for (int k = 0; k < 2; ++k) \
;         acc[ai][bj][m][n] = __builtin_amdgcn_mfma_f32_16x16x32_bf16(Bt[n][k], At[m][k], acc[ai][bj][m][n], 0, 0, 0); __builtin_amdgcn_s_setprio(0); } while (0)
; #define PG8_WAIT_V(n) asm volatile("s_waitcnt vmcnt(" #n ")" ::: "memory")
; #define PG8_WAIT_L(n) asm volatile("s_waitcnt lgkmcnt(" #n ")" ::: "memory")
; #define PG8_BAR __builtin_amdgcn_s_barrier()
; #define PG8_SCHED __builtin_amdgcn_sched_barrier(0)
; template <class Epi, class Sched, bool ALIGN_EPI = false, bool SP2 = false>
; __device__ __forceinline__ void gemm_phase(PG8_LAS unsigned char* lds, const Gemm g, const Sched S, const Epi E) {
;     ...
;             PG8_LDA(At, 1, 1); PG8_STAGE(PG8_SB(1, 0), b3, voffB); PG8_STAGE(PG8_SB(1, 1), b3 + hstep, voffB); PG8_STAGE(PG8_SA(1, 0), a3, voffA);
;             PG8_WAIT_V(8); PG8_WAIT_L(0); PG8_BAR; PG8_MMA(1, 0, At, B0); PG8_MMA(1, 1, At, B1); PG8_BAR; PG8_SCHED;
	s_add_i32 s20, s20, s84
	v_lshl_add_u64 v[234:235], v[234:235], 0, s[12:13]
	s_mov_b32 m0, s20
	ds_read_b128 v[202:205], v152 offset:49152
	ds_read_b128 v[206:209], v152 offset:50176
	ds_read_b128 v[210:213], v152 offset:51200
	ds_read_b128 v[214:217], v152 offset:52224
	ds_read_b128 v[218:221], v152 offset:53248
	ds_read_b128 v[222:225], v152 offset:54272
	ds_read_b128 v[226:229], v152 offset:55296
	ds_read_b128 v[230:233], v152 offset:56320
	global_load_lds_dwordx4 v[234:235], off
	v_lshl_add_u64 v[234:235], v[236:237], 0, s[12:13]
	s_add_i32 m0, s20, 0x2000
	s_add_i32 s20, s26, s84
	global_load_lds_dwordx4 v[234:235], off
	v_lshl_add_u64 v[234:235], v[238:239], 0, s[12:13]
	s_mov_b32 m0, s20
	s_nop 0
	global_load_lds_dwordx4 v[234:235], off
	v_lshl_add_u64 v[234:235], v[240:241], 0, s[12:13]
	s_add_i32 m0, s20, 0x2000
	s_nop 0
	global_load_lds_dwordx4 v[234:235], off
	v_lshl_add_u64 v[234:235], v[242:243], 0, s[12:13]
	s_mov_b32 m0, s3
	s_nop 0
	global_load_lds_dwordx4 v[234:235], off
	v_lshl_add_u64 v[234:235], v[244:245], 0, s[12:13]
	s_mov_b32 m0, s24
	s_nop 0
	global_load_lds_dwordx4 v[234:235], off
	s_waitcnt vmcnt(8) lgkmcnt(0)
	s_barrier
	s_setprio 1
	v_mfma_f32_16x16x32_bf16 v[62:65], v[154:157], v[202:205], v[62:65]
	v_mfma_f32_16x16x32_bf16 v[58:61], v[162:165], v[202:205], v[58:61]
	v_mfma_f32_16x16x32_bf16 v[46:49], v[154:157], v[210:213], v[46:49]
	v_mfma_f32_16x16x32_bf16 v[42:45], v[162:165], v[210:213], v[42:45]
	v_mfma_f32_16x16x32_bf16 v[30:33], v[154:157], v[218:221], v[30:33]
	v_mfma_f32_16x16x32_bf16 v[26:29], v[162:165], v[218:221], v[26:29]
	v_mfma_f32_16x16x32_bf16 v[14:17], v[154:157], v[226:229], v[14:17]
	v_mfma_f32_16x16x32_bf16 v[10:13], v[162:165], v[226:229], v[10:13]
	v_mfma_f32_16x16x32_bf16 v[62:65], v[158:161], v[206:209], v[62:65]
	v_mfma_f32_16x16x32_bf16 v[58:61], v[166:169], v[206:209], v[58:61]
	v_mfma_f32_16x16x32_bf16 v[46:49], v[158:161], v[214:217], v[46:49]
	v_mfma_f32_16x16x32_bf16 v[42:45], v[166:169], v[214:217], v[42:45]
	v_mfma_f32_16x16x32_bf16 v[30:33], v[158:161], v[222:225], v[30:33]
	v_mfma_f32_16x16x32_bf16 v[26:29], v[166:169], v[222:225], v[26:29]
	v_mfma_f32_16x16x32_bf16 v[14:17], v[158:161], v[230:233], v[14:17]
	v_mfma_f32_16x16x32_bf16 v[10:13], v[166:169], v[230:233], v[10:13]
	v_mfma_f32_16x16x32_bf16 v[54:57], v[170:173], v[202:205], v[54:57]
	v_mfma_f32_16x16x32_bf16 v[50:53], v[182:185], v[202:205], v[50:53]
	v_mfma_f32_16x16x32_bf16 v[38:41], v[170:173], v[210:213], v[38:41]
	v_mfma_f32_16x16x32_bf16 v[34:37], v[182:185], v[210:213], v[34:37]
	v_mfma_f32_16x16x32_bf16 v[22:25], v[170:173], v[218:221], v[22:25]
	v_mfma_f32_16x16x32_bf16 v[18:21], v[182:185], v[218:221], v[18:21]
	v_mfma_f32_16x16x32_bf16 v[6:9], v[170:173], v[226:229], v[6:9]
	v_mfma_f32_16x16x32_bf16 v[2:5], v[182:185], v[226:229], v[2:5]
	v_mfma_f32_16x16x32_bf16 v[54:57], v[174:177], v[206:209], v[54:57]
	v_mfma_f32_16x16x32_bf16 v[50:53], v[198:201], v[206:209], v[50:53]
	v_mfma_f32_16x16x32_bf16 v[38:41], v[174:177], v[214:217], v[38:41]
	v_mfma_f32_16x16x32_bf16 v[34:37], v[198:201], v[214:217], v[34:37]
	v_mfma_f32_16x16x32_bf16 v[22:25], v[174:177], v[222:225], v[22:25]
	v_mfma_f32_16x16x32_bf16 v[18:21], v[198:201], v[222:225], v[18:21]
	v_mfma_f32_16x16x32_bf16 v[6:9], v[174:177], v[230:233], v[6:9]
	v_mfma_f32_16x16x32_bf16 v[2:5], v[198:201], v[230:233], v[2:5]
	s_setprio 0
	s_add_u32 s30, s30, 0x100
	s_addc_u32 s31, s31, 0
	s_add_u32 s14, s14, 0x100
	s_addc_u32 s15, s15, 0
	s_cmp_ge_u32 s21, s80
	s_mov_b32 s20, s21
	s_barrier
	s_cbranch_scc0 .LBB0_224
	s_and_b64 vcc, exec, s[16:17]
	s_cbranch_vccz .LBB0_227
	s_barrier

; #define PG8_STAGE(bufoff, gbase, voff) do { _Pragma("unroll") for (int _i = 0; _i < 2; ++_i) \
;         __builtin_amdgcn_global_load_lds((const unsigned*)((const char*)(gbase) + (voff)[_i]), (PG8_LAS unsigned*)(lds + (bufoff) + ldsw + _i * 8192), 16, 0, 0); } while (0)
; #define PG8_LDA(dst, b, h) do { _Pragma("unroll") for (int m = 0; m < 4; ++m) _Pragma("unroll") for (int k = 0; k < 2; ++k) dst[m][k] = *(const PG8_LAS bf16x8*)(lds + PG8_SA(b, h) + aoff + m * 2048 + k * 1024); } while (0)
; #define PG8_LDB(dst, b, h) do { _Pragma("unroll") for (int n = 0; n < 2; ++n) _Pragma("unroll") for (int k = 0; k < 2; ++k) dst[n][k] = *(const PG8_LAS bf16x8*)(lds + PG8_SB(b, h) + boff + n * 2048 + k * 1024); } while (0)
; #define PG8_MMA(ai, bj, At, Bt) do { __builtin_amdgcn_s_setprio(1); _Pragma("unroll") for (int m = 0; m < 4; ++m) _Pragma("unroll") for (int n = 0; n < 2; ++n) _Pragma("unroll") for (int k = 0; k < 2; ++k) \
;         acc[ai][bj][m][n] = __builtin_amdgcn_mfma_f32_16x16x32_bf16(Bt[n][k], At[m][k], acc[ai][bj][m][n], 0, 0, 0); __builtin_amdgcn_s_setprio(0); } while (0)
; #define PG8_WAIT_V(n) asm volatile("s_waitcnt vmcnt(" #n ")" ::: "memory")
; #define PG8_WAIT_L(n) asm volatile("s_waitcnt lgkmcnt(" #n ")" ::: "memory")
; #define PG8_BAR __builtin_amdgcn_s_barrier()
; #define PG8_SCHED __builtin_amdgcn_sched_barrier(0)
; template <class Epi, class Sched, bool ALIGN_EPI = false, bool SP2 = false>
; __device__ __forceinline__ void gemm_phase(PG8_LAS unsigned char* lds, const Gemm g, const Sched S, const Epi E) {
;     ...
;             PG8_LDB(B0, 0, 0); PG8_LDB(B1, 0, 1); PG8_SCHED; PG8_LDA(At, 0, 0); PG8_STAGE(PG8_SA(1, 1), a1 + hstep, voffA);
;             PG8_WAIT_V(8); PG8_WAIT_L(0); PG8_BAR; PG8_MMA(0, 0, At, B0); PG8_MMA(0, 1, At, B1); PG8_BAR; PG8_SCHED;
;             PG8_LDA(At, 0, 1); PG8_STAGE(PG8_SB(0, 0), b2, voffB); PG8_STAGE(PG8_SB(0, 1), b2 + hstep, voffB); PG8_STAGE(PG8_SA(0, 0), a2, voffA);
;             PG8_WAIT_V(8); PG8_WAIT_L(0); PG8_BAR; PG8_MMA(1, 0, At, B0); PG8_MMA(1, 1, At, B1); PG8_BAR; PG8_SCHED;
.LBB0_416:
	v_add_u32_e32 v158, 0x10000, v168
	v_add_u32_e32 v171, 0x14000, v168
	ds_read_b128 v[134:137], v158
	ds_read_b128 v[138:141], v158 offset:1024
	ds_read_b128 v[142:145], v158 offset:2048
	ds_read_b128 v[158:161], v158 offset:3072
	ds_read_b128 v[162:165], v171
	ds_read_b128 v[172:175], v171 offset:1024
	ds_read_b128 v[182:185], v171 offset:2048
	ds_read_b128 v[198:201], v171 offset:3072
	s_add_i32 s3, s14, 2
	s_add_u32 s15, s68, s16
	s_addc_u32 s18, s69, s17
	s_add_u32 s20, s66, s16
	s_addc_u32 s21, s67, s17
	s_add_i32 s22, 0, 0x10000
	s_cmp_eq_u32 s89, s14
	s_cselect_b32 s19, s1, s18
	s_cselect_b32 s18, s0, s15
	s_cselect_b32 s15, s71, s21
	s_cselect_b32 s14, s70, s20
	s_add_i32 s20, 0, 0x14000
	v_lshl_add_u64 v[176:177], s[68:69], 0, v[132:133]
	s_add_i32 m0, s80, 0xc000
	ds_read_b128 v[202:205], v170
	ds_read_b128 v[206:209], v170 offset:1024
	ds_read_b128 v[210:213], v170 offset:2048
	ds_read_b128 v[214:217], v170 offset:3072
	ds_read_b128 v[218:221], v170 offset:4096
	ds_read_b128 v[222:225], v170 offset:5120
	ds_read_b128 v[226:229], v170 offset:6144
	ds_read_b128 v[230:233], v170 offset:7168
	global_load_lds_dwordx4 v[176:177], off
	v_lshl_add_u64 v[176:177], s[68:69], 0, v[130:131]
	s_add_i32 m0, s80, 0xe000
	s_nop 0
	global_load_lds_dwordx4 v[176:177], off
	s_waitcnt vmcnt(8) lgkmcnt(0)
	s_barrier
	s_setprio 1
	v_mfma_f32_16x16x32_bf16 v[58:61], v[134:137], v[202:205], v[58:61]
	v_mfma_f32_16x16x32_bf16 v[50:53], v[142:145], v[202:205], v[50:53]
	v_mfma_f32_16x16x32_bf16 v[14:17], v[134:137], v[210:213], v[14:17]
	v_mfma_f32_16x16x32_bf16 v[10:13], v[142:145], v[210:213], v[10:13]
	v_mfma_f32_16x16x32_bf16 v[30:33], v[134:137], v[218:221], v[30:33]
	v_mfma_f32_16x16x32_bf16 v[26:29], v[142:145], v[218:221], v[26:29]
	v_mfma_f32_16x16x32_bf16 v[46:49], v[134:137], v[226:229], v[46:49]
	v_mfma_f32_16x16x32_bf16 v[42:45], v[142:145], v[226:229], v[42:45]
	v_mfma_f32_16x16x32_bf16 v[58:61], v[138:141], v[206:209], v[58:61]
	v_mfma_f32_16x16x32_bf16 v[50:53], v[158:161], v[206:209], v[50:53]
	v_mfma_f32_16x16x32_bf16 v[14:17], v[138:141], v[214:217], v[14:17]
	v_mfma_f32_16x16x32_bf16 v[10:13], v[158:161], v[214:217], v[10:13]
	v_mfma_f32_16x16x32_bf16 v[30:33], v[138:141], v[222:225], v[30:33]
	v_mfma_f32_16x16x32_bf16 v[26:29], v[158:161], v[222:225], v[26:29]
	v_mfma_f32_16x16x32_bf16 v[46:49], v[138:141], v[230:233], v[46:49]
	v_mfma_f32_16x16x32_bf16 v[42:45], v[158:161], v[230:233], v[42:45]
	v_mfma_f32_16x16x32_bf16 v[6:9], v[162:165], v[202:205], v[6:9]
	v_mfma_f32_16x16x32_bf16 v[2:5], v[182:185], v[202:205], v[2:5]
	v_mfma_f32_16x16x32_bf16 v[22:25], v[162:165], v[210:213], v[22:25]
	v_mfma_f32_16x16x32_bf16 v[18:21], v[182:185], v[210:213], v[18:21]
	v_mfma_f32_16x16x32_bf16 v[38:41], v[162:165], v[218:221], v[38:41]
	v_mfma_f32_16x16x32_bf16 v[34:37], v[182:185], v[218:221], v[34:37]
	v_mfma_f32_16x16x32_bf16 v[62:65], v[162:165], v[226:229], v[62:65]
	v_mfma_f32_16x16x32_bf16 v[54:57], v[182:185], v[226:229], v[54:57]
	v_mfma_f32_16x16x32_bf16 v[6:9], v[172:175], v[206:209], v[6:9]
	v_mfma_f32_16x16x32_bf16 v[2:5], v[198:201], v[206:209], v[2:5]
	v_mfma_f32_16x16x32_bf16 v[22:25], v[172:175], v[214:217], v[22:25]
	v_mfma_f32_16x16x32_bf16 v[18:21], v[198:201], v[214:217], v[18:21]
	v_mfma_f32_16x16x32_bf16 v[38:41], v[172:175], v[222:225], v[38:41]
	v_mfma_f32_16x16x32_bf16 v[34:37], v[198:201], v[222:225], v[34:37]
	v_mfma_f32_16x16x32_bf16 v[62:65], v[172:175], v[230:233], v[62:65]
	v_mfma_f32_16x16x32_bf16 v[54:57], v[198:201], v[230:233], v[54:57]
	s_setprio 0
	s_barrier
	s_add_i32 s21, s22, s79
	v_lshl_add_u64 v[176:177], s[14:15], 0, v[148:149]
	s_mov_b32 m0, s21
	ds_read_b128 v[202:205], v170 offset:16384
	ds_read_b128 v[206:209], v170 offset:17408
	ds_read_b128 v[210:213], v170 offset:18432
	ds_read_b128 v[214:217], v170 offset:19456
	ds_read_b128 v[218:221], v170 offset:20480
	ds_read_b128 v[222:225], v170 offset:21504
	ds_read_b128 v[226:229], v170 offset:22528
	ds_read_b128 v[230:233], v170 offset:23552
	global_load_lds_dwordx4 v[176:177], off
	s_add_i32 m0, s21, 0x2000
	v_lshl_add_u64 v[234:235], s[14:15], 0, v[152:153]
	s_add_u32 s14, s14, s28
	s_addc_u32 s15, s15, 0
	s_add_i32 s20, s20, s79
	global_load_lds_dwordx4 v[234:235], off
	v_lshl_add_u64 v[236:237], s[14:15], 0, v[148:149]
	s_mov_b32 m0, s20
	v_lshl_add_u64 v[238:239], s[14:15], 0, v[152:153]
	global_load_lds_dwordx4 v[236:237], off
	s_add_i32 m0, s20, 0x2000
	v_lshl_add_u64 v[240:241], s[18:19], 0, v[146:147]
	global_load_lds_dwordx4 v[238:239], off
	s_mov_b32 m0, s80
	v_lshl_add_u64 v[242:243], s[18:19], 0, v[150:151]
	global_load_lds_dwordx4 v[240:241], off
	s_mov_b32 m0, s81
	s_nop 0
	global_load_lds_dwordx4 v[242:243], off
	s_waitcnt vmcnt(8) lgkmcnt(0)
	s_barrier
; #define PG8_STAGE(bufoff, gbase, voff) do { _Pragma("unroll") for (int _i = 0; _i < 2; ++_i) \
;         __builtin_amdgcn_global_load_lds((const unsigned*)((const char*)(gbase) + (voff)[_i]), (PG8_LAS unsigned*)(lds + (bufoff) + ldsw + _i * 8192), 16, 0, 0); } while (0)
; #define PG8_LDA(dst, b, h) do { _Pragma("unroll") for (int m = 0; m < 4; ++m) _Pragma("unroll") for (int k = 0; k < 2; ++k) dst[m][k] = *(const PG8_LAS bf16x8*)(lds + PG8_SA(b, h) + aoff + m * 2048 + k * 1024); } while (0)
; #define PG8_LDB(dst, b, h) do { _Pragma("unroll") for (int n = 0; n < 2; ++n) _Pragma("unroll") for (int k = 0; k < 2; ++k) dst[n][k] = *(const PG8_LAS bf16x8*)(lds + PG8_SB(b, h) + boff + n * 2048 + k * 1024); } while (0)
; #define PG8_MMA(ai, bj, At, Bt) do { __builtin_amdgcn_s_setprio(1); _Pragma("unroll") for (int m = 0; m < 4; ++m) _Pragma("unroll") for (int n = 0; n < 2; ++n) _Pragma("unroll") for (int k = 0; k < 2; ++k) \
;         acc[ai][bj][m][n] = __builtin_amdgcn_mfma_f32_16x16x32_bf16(Bt[n][k], At[m][k], acc[ai][bj][m][n], 0, 0, 0); __builtin_amdgcn_s_setprio(0); } while (0)
; #define PG8_WAIT_V(n) asm volatile("s_waitcnt vmcnt(" #n ")" ::: "memory")
; #define PG8_WAIT_L(n) asm volatile("s_waitcnt lgkmcnt(" #n ")" ::: "memory")
; #define PG8_BAR __builtin_amdgcn_s_barrier()
; #define PG8_SCHED __builtin_amdgcn_sched_barrier(0)
; template <class Epi, class Sched, bool ALIGN_EPI = false, bool SP2 = false>
; __device__ __forceinline__ void gemm_phase(PG8_LAS unsigned char* lds, const Gemm g, const Sched S, const Epi E) {
;     ...
;             PG8_WAIT_V(8); PG8_WAIT_L(0); PG8_BAR; PG8_MMA(1, 0, At, B0); PG8_MMA(1, 1, At, B1); PG8_BAR; PG8_SCHED;
;             PG8_LDB(B0, 1, 0); PG8_LDB(B1, 1, 1); PG8_SCHED; PG8_LDA(At, 1, 0); PG8_STAGE(PG8_SA(0, 1), a2 + hstep, voffA);
;             PG8_WAIT_V(8); PG8_WAIT_L(0); PG8_BAR; PG8_MMA(0, 0, At, B0); PG8_MMA(0, 1, At, B1); PG8_BAR; PG8_SCHED;
	s_setprio 1
	v_mfma_f32_16x16x32_bf16 v[70:73], v[134:137], v[202:205], v[70:73]
	v_mfma_f32_16x16x32_bf16 v[66:69], v[142:145], v[202:205], v[66:69]
	v_mfma_f32_16x16x32_bf16 v[86:89], v[134:137], v[210:213], v[86:89]
	v_mfma_f32_16x16x32_bf16 v[82:85], v[142:145], v[210:213], v[82:85]
	v_mfma_f32_16x16x32_bf16 v[102:105], v[134:137], v[218:221], v[102:105]
	v_mfma_f32_16x16x32_bf16 v[98:101], v[142:145], v[218:221], v[98:101]
	v_mfma_f32_16x16x32_bf16 v[118:121], v[134:137], v[226:229], v[118:121]
	v_mfma_f32_16x16x32_bf16 v[114:117], v[142:145], v[226:229], v[114:117]
	v_mfma_f32_16x16x32_bf16 v[70:73], v[138:141], v[206:209], v[70:73]
	v_mfma_f32_16x16x32_bf16 v[66:69], v[158:161], v[206:209], v[66:69]
	v_mfma_f32_16x16x32_bf16 v[86:89], v[138:141], v[214:217], v[86:89]
	v_mfma_f32_16x16x32_bf16 v[82:85], v[158:161], v[214:217], v[82:85]
	v_mfma_f32_16x16x32_bf16 v[102:105], v[138:141], v[222:225], v[102:105]
	v_mfma_f32_16x16x32_bf16 v[98:101], v[158:161], v[222:225], v[98:101]
	v_mfma_f32_16x16x32_bf16 v[118:121], v[138:141], v[230:233], v[118:121]
	v_mfma_f32_16x16x32_bf16 v[114:117], v[158:161], v[230:233], v[114:117]
	v_mfma_f32_16x16x32_bf16 v[78:81], v[162:165], v[202:205], v[78:81]
	v_mfma_f32_16x16x32_bf16 v[74:77], v[182:185], v[202:205], v[74:77]
	v_mfma_f32_16x16x32_bf16 v[94:97], v[162:165], v[210:213], v[94:97]
	v_mfma_f32_16x16x32_bf16 v[90:93], v[182:185], v[210:213], v[90:93]
	v_mfma_f32_16x16x32_bf16 v[110:113], v[162:165], v[218:221], v[110:113]
	v_mfma_f32_16x16x32_bf16 v[106:109], v[182:185], v[218:221], v[106:109]
	v_mfma_f32_16x16x32_bf16 v[126:129], v[162:165], v[226:229], v[126:129]
	v_mfma_f32_16x16x32_bf16 v[122:125], v[182:185], v[226:229], v[122:125]
	v_mfma_f32_16x16x32_bf16 v[78:81], v[172:175], v[206:209], v[78:81]
	v_mfma_f32_16x16x32_bf16 v[74:77], v[198:201], v[206:209], v[74:77]
	v_mfma_f32_16x16x32_bf16 v[94:97], v[172:175], v[214:217], v[94:97]
	v_mfma_f32_16x16x32_bf16 v[90:93], v[198:201], v[214:217], v[90:93]
	v_mfma_f32_16x16x32_bf16 v[110:113], v[172:175], v[222:225], v[110:113]
	v_mfma_f32_16x16x32_bf16 v[106:109], v[198:201], v[222:225], v[106:109]
	v_mfma_f32_16x16x32_bf16 v[126:129], v[172:175], v[230:233], v[126:129]
	v_mfma_f32_16x16x32_bf16 v[122:125], v[198:201], v[230:233], v[122:125]
	s_setprio 0
	s_barrier
	v_add_u32_e32 v158, 0x18000, v168
	v_add_u32_e32 v171, 0x1c000, v168
	ds_read_b128 v[134:137], v158
	ds_read_b128 v[138:141], v158 offset:1024
	ds_read_b128 v[142:145], v158 offset:2048
	ds_read_b128 v[158:161], v158 offset:3072
	ds_read_b128 v[162:165], v171
	ds_read_b128 v[172:175], v171 offset:1024
	ds_read_b128 v[182:185], v171 offset:2048
	ds_read_b128 v[198:201], v171 offset:3072
	s_add_i32 s20, 0, 0x18000
	s_add_i32 s21, 0, 0x1c000
	s_add_u32 s14, s18, s28
	s_addc_u32 s15, s19, 0
	s_mov_b32 m0, s82
	v_lshl_add_u64 v[244:245], s[14:15], 0, v[146:147]
	ds_read_b128 v[202:205], v170 offset:32768
	ds_read_b128 v[206:209], v170 offset:33792
	ds_read_b128 v[210:213], v170 offset:34816
	ds_read_b128 v[214:217], v170 offset:35840
	ds_read_b128 v[218:221], v170 offset:36864
	ds_read_b128 v[222:225], v170 offset:37888
	ds_read_b128 v[226:229], v170 offset:38912
	ds_read_b128 v[230:233], v170 offset:39936
	global_load_lds_dwordx4 v[244:245], off
	v_lshl_add_u64 v[244:245], s[14:15], 0, v[150:151]
	s_mov_b32 m0, s83
	s_nop 0
	global_load_lds_dwordx4 v[244:245], off
	s_waitcnt vmcnt(8) lgkmcnt(0)
	s_barrier
	s_setprio 1
	v_mfma_f32_16x16x32_bf16 v[58:61], v[134:137], v[202:205], v[58:61]
	v_mfma_f32_16x16x32_bf16 v[50:53], v[142:145], v[202:205], v[50:53]
	v_mfma_f32_16x16x32_bf16 v[14:17], v[134:137], v[210:213], v[14:17]
	v_mfma_f32_16x16x32_bf16 v[10:13], v[142:145], v[210:213], v[10:13]
	v_mfma_f32_16x16x32_bf16 v[30:33], v[134:137], v[218:221], v[30:33]
	v_mfma_f32_16x16x32_bf16 v[26:29], v[142:145], v[218:221], v[26:29]
	v_mfma_f32_16x16x32_bf16 v[46:49], v[134:137], v[226:229], v[46:49]
	v_mfma_f32_16x16x32_bf16 v[42:45], v[142:145], v[226:229], v[42:45]
	v_mfma_f32_16x16x32_bf16 v[58:61], v[138:141], v[206:209], v[58:61]
	v_mfma_f32_16x16x32_bf16 v[50:53], v[158:161], v[206:209], v[50:53]
	v_mfma_f32_16x16x32_bf16 v[14:17], v[138:141], v[214:217], v[14:17]
	v_mfma_f32_16x16x32_bf16 v[10:13], v[158:161], v[214:217], v[10:13]
	v_mfma_f32_16x16x32_bf16 v[30:33], v[138:141], v[222:225], v[30:33]
	v_mfma_f32_16x16x32_bf16 v[26:29], v[158:161], v[222:225], v[26:29]
	v_mfma_f32_16x16x32_bf16 v[46:49], v[138:141], v[230:233], v[46:49]
	v_mfma_f32_16x16x32_bf16 v[42:45], v[158:161], v[230:233], v[42:45]
	v_mfma_f32_16x16x32_bf16 v[6:9], v[162:165], v[202:205], v[6:9]
	v_mfma_f32_16x16x32_bf16 v[2:5], v[182:185], v[202:205], v[2:5]
	v_mfma_f32_16x16x32_bf16 v[22:25], v[162:165], v[210:213], v[22:25]
	v_mfma_f32_16x16x32_bf16 v[18:21], v[182:185], v[210:213], v[18:21]
	v_mfma_f32_16x16x32_bf16 v[38:41], v[162:165], v[218:221], v[38:41]
	v_mfma_f32_16x16x32_bf16 v[34:37], v[182:185], v[218:221], v[34:37]
	v_mfma_f32_16x16x32_bf16 v[62:65], v[162:165], v[226:229], v[62:65]
	v_mfma_f32_16x16x32_bf16 v[54:57], v[182:185], v[226:229], v[54:57]
	v_mfma_f32_16x16x32_bf16 v[6:9], v[172:175], v[206:209], v[6:9]
	v_mfma_f32_16x16x32_bf16 v[2:5], v[198:201], v[206:209], v[2:5]
	v_mfma_f32_16x16x32_bf16 v[22:25], v[172:175], v[214:217], v[22:25]
	v_mfma_f32_16x16x32_bf16 v[18:21], v[198:201], v[214:217], v[18:21]
	v_mfma_f32_16x16x32_bf16 v[38:41], v[172:175], v[222:225], v[38:41]
	v_mfma_f32_16x16x32_bf16 v[34:37], v[198:201], v[222:225], v[34:37]
	v_mfma_f32_16x16x32_bf16 v[62:65], v[172:175], v[230:233], v[62:65]
	v_mfma_f32_16x16x32_bf16 v[54:57], v[198:201], v[230:233], v[54:57]
	s_setprio 0
	s_barrier
; #define PG8_STAGE(bufoff, gbase, voff) do { _Pragma("unroll") for (int _i = 0; _i < 2; ++_i) \
;         __builtin_amdgcn_global_load_lds((const unsigned*)((const char*)(gbase) + (voff)[_i]), (PG8_LAS unsigned*)(lds + (bufoff) + ldsw + _i * 8192), 16, 0, 0); } while (0)
; #define PG8_LDA(dst, b, h) do { _Pragma("unroll") for (int m = 0; m < 4; ++m) _Pragma("unroll") for (int k = 0; k < 2; ++k) dst[m][k] = *(const PG8_LAS bf16x8*)(lds + PG8_SA(b, h) + aoff + m * 2048 + k * 1024); } while (0)
; #define PG8_MMA(ai, bj, At, Bt) do { __builtin_amdgcn_s_setprio(1); _Pragma("unroll") for (int m = 0; m < 4; ++m) _Pragma("unroll") for (int n = 0; n < 2; ++n) _Pragma("unroll") for (int k = 0; k < 2; ++k) \
;         acc[ai][bj][m][n] = __builtin_amdgcn_mfma_f32_16x16x32_bf16(Bt[n][k], At[m][k], acc[ai][bj][m][n], 0, 0, 0); __builtin_amdgcn_s_setprio(0); } while (0)
; #define PG8_WAIT_V(n) asm volatile("s_waitcnt vmcnt(" #n ")" ::: "memory")
; #define PG8_WAIT_L(n) asm volatile("s_waitcnt lgkmcnt(" #n ")" ::: "memory")
; #define PG8_BAR __builtin_amdgcn_s_barrier()
; #define PG8_SCHED __builtin_amdgcn_sched_barrier(0)
; template <class Epi, class Sched, bool ALIGN_EPI = false, bool SP2 = false>
; __device__ __forceinline__ void gemm_phase(PG8_LAS unsigned char* lds, const Gemm g, const Sched S, const Epi E) {
;     ...
;             PG8_LDA(At, 1, 1); PG8_STAGE(PG8_SB(1, 0), b3, voffB); PG8_STAGE(PG8_SB(1, 1), b3 + hstep, voffB); PG8_STAGE(PG8_SA(1, 0), a3, voffA);
;             PG8_WAIT_V(8); PG8_WAIT_L(0); PG8_BAR; PG8_MMA(1, 0, At, B0); PG8_MMA(1, 1, At, B1); PG8_BAR; PG8_SCHED;
	s_add_i32 s14, s20, s79
	v_lshl_add_u64 v[176:177], v[176:177], 0, s[12:13]
	s_mov_b32 m0, s14
	ds_read_b128 v[202:205], v170 offset:49152
	ds_read_b128 v[206:209], v170 offset:50176
	ds_read_b128 v[210:213], v170 offset:51200
	ds_read_b128 v[214:217], v170 offset:52224
	ds_read_b128 v[218:221], v170 offset:53248
	ds_read_b128 v[222:225], v170 offset:54272
	ds_read_b128 v[226:229], v170 offset:55296
	ds_read_b128 v[230:233], v170 offset:56320
	global_load_lds_dwordx4 v[176:177], off
	v_lshl_add_u64 v[176:177], v[234:235], 0, s[12:13]
	s_add_i32 m0, s14, 0x2000
	s_add_i32 s14, s21, s79
	global_load_lds_dwordx4 v[176:177], off
	v_lshl_add_u64 v[176:177], v[236:237], 0, s[12:13]
	s_mov_b32 m0, s14
	s_nop 0
	global_load_lds_dwordx4 v[176:177], off
	v_lshl_add_u64 v[176:177], v[238:239], 0, s[12:13]
	s_add_i32 m0, s14, 0x2000
	s_nop 0
	global_load_lds_dwordx4 v[176:177], off
	v_lshl_add_u64 v[176:177], v[240:241], 0, s[12:13]
	s_mov_b32 m0, s84
	s_nop 0
	global_load_lds_dwordx4 v[176:177], off
	v_lshl_add_u64 v[176:177], v[242:243], 0, s[12:13]
	s_mov_b32 m0, s85
	s_nop 0
	global_load_lds_dwordx4 v[176:177], off
	s_waitcnt vmcnt(8) lgkmcnt(0)
	s_barrier
	s_setprio 1
	v_mfma_f32_16x16x32_bf16 v[70:73], v[134:137], v[202:205], v[70:73]
	v_mfma_f32_16x16x32_bf16 v[66:69], v[142:145], v[202:205], v[66:69]
	v_mfma_f32_16x16x32_bf16 v[86:89], v[134:137], v[210:213], v[86:89]
	v_mfma_f32_16x16x32_bf16 v[82:85], v[142:145], v[210:213], v[82:85]
	v_mfma_f32_16x16x32_bf16 v[102:105], v[134:137], v[218:221], v[102:105]
	v_mfma_f32_16x16x32_bf16 v[98:101], v[142:145], v[218:221], v[98:101]
	v_mfma_f32_16x16x32_bf16 v[118:121], v[134:137], v[226:229], v[118:121]
	v_mfma_f32_16x16x32_bf16 v[114:117], v[142:145], v[226:229], v[114:117]
	v_mfma_f32_16x16x32_bf16 v[70:73], v[138:141], v[206:209], v[70:73]
	v_mfma_f32_16x16x32_bf16 v[66:69], v[158:161], v[206:209], v[66:69]
	v_mfma_f32_16x16x32_bf16 v[86:89], v[138:141], v[214:217], v[86:89]
	v_mfma_f32_16x16x32_bf16 v[82:85], v[158:161], v[214:217], v[82:85]
	v_mfma_f32_16x16x32_bf16 v[102:105], v[138:141], v[222:225], v[102:105]
	v_mfma_f32_16x16x32_bf16 v[98:101], v[158:161], v[222:225], v[98:101]
	v_mfma_f32_16x16x32_bf16 v[118:121], v[138:141], v[230:233], v[118:121]
	v_mfma_f32_16x16x32_bf16 v[114:117], v[158:161], v[230:233], v[114:117]
	v_mfma_f32_16x16x32_bf16 v[78:81], v[162:165], v[202:205], v[78:81]
	v_mfma_f32_16x16x32_bf16 v[74:77], v[182:185], v[202:205], v[74:77]
	v_mfma_f32_16x16x32_bf16 v[94:97], v[162:165], v[210:213], v[94:97]
	v_mfma_f32_16x16x32_bf16 v[90:93], v[182:185], v[210:213], v[90:93]
	v_mfma_f32_16x16x32_bf16 v[110:113], v[162:165], v[218:221], v[110:113]
	v_mfma_f32_16x16x32_bf16 v[106:109], v[182:185], v[218:221], v[106:109]
	v_mfma_f32_16x16x32_bf16 v[126:129], v[162:165], v[226:229], v[126:129]
	v_mfma_f32_16x16x32_bf16 v[122:125], v[182:185], v[226:229], v[122:125]
	v_mfma_f32_16x16x32_bf16 v[78:81], v[172:175], v[206:209], v[78:81]
	v_mfma_f32_16x16x32_bf16 v[74:77], v[198:201], v[206:209], v[74:77]
	v_mfma_f32_16x16x32_bf16 v[94:97], v[172:175], v[214:217], v[94:97]
	v_mfma_f32_16x16x32_bf16 v[90:93], v[198:201], v[214:217], v[90:93]
	v_mfma_f32_16x16x32_bf16 v[110:113], v[172:175], v[222:225], v[110:113]
	v_mfma_f32_16x16x32_bf16 v[106:109], v[198:201], v[222:225], v[106:109]
	v_mfma_f32_16x16x32_bf16 v[126:129], v[172:175], v[230:233], v[126:129]
	v_mfma_f32_16x16x32_bf16 v[122:125], v[198:201], v[230:233], v[122:125]
	s_setprio 0
	s_add_u32 s16, s16, 0x100
	s_addc_u32 s17, s17, 0
	v_lshl_add_u64 v[132:133], v[132:133], 0, s[30:31]
	v_lshl_add_u64 v[130:131], v[130:131], 0, s[30:31]
	s_cmp_ge_u32 s3, s88
	s_mov_b32 s14, s3
	s_barrier
	s_cbranch_scc0 .LBB0_416
	s_and_b64 vcc, exec, s[62:63]
	s_cbranch_vccz .LBB0_419
	s_barrier

; #define PG8_STAGE(bufoff, gbase, voff) do { _Pragma("unroll") for (int _i = 0; _i < 2; ++_i) \
;         __builtin_amdgcn_global_load_lds((const unsigned*)((const char*)(gbase) + (voff)[_i]), (PG8_LAS unsigned*)(lds + (bufoff) + ldsw + _i * 8192), 16, 0, 0); } while (0)
; #define PG8_LDA(dst, b, h) do { _Pragma("unroll") for (int m = 0; m < 4; ++m) _Pragma("unroll") for (int k = 0; k < 2; ++k) dst[m][k] = *(const PG8_LAS bf16x8*)(lds + PG8_SA(b, h) + aoff + m * 2048 + k * 1024); } while (0)
; #define PG8_LDB(dst, b, h) do { _Pragma("unroll") for (int n = 0; n < 2; ++n) _Pragma("unroll") for (int k = 0; k < 2; ++k) dst[n][k] = *(const PG8_LAS bf16x8*)(lds + PG8_SB(b, h) + boff + n * 2048 + k * 1024); } while (0)
; #define PG8_MMA(ai, bj, At, Bt) do { __builtin_amdgcn_s_setprio(1); _Pragma("unroll") for (int m = 0; m < 4; ++m) _Pragma("unroll") for (int n = 0; n < 2; ++n) _Pragma("unroll") for (int k = 0; k < 2; ++k) \
;         acc[ai][bj][m][n] = __builtin_amdgcn_mfma_f32_16x16x32_bf16(Bt[n][k], At[m][k], acc[ai][bj][m][n], 0, 0, 0); __builtin_amdgcn_s_setprio(0); } while (0)
; #define PG8_WAIT_V(n) asm volatile("s_waitcnt vmcnt(" #n ")" ::: "memory")
; #define PG8_WAIT_L(n) asm volatile("s_waitcnt lgkmcnt(" #n ")" ::: "memory")
; #define PG8_BAR __builtin_amdgcn_s_barrier()
; #define PG8_SCHED __builtin_amdgcn_sched_barrier(0)
; template <class Epi, class Sched, bool ALIGN_EPI = false, bool SP2 = false>
; __device__ __forceinline__ void gemm_phase(PG8_LAS unsigned char* lds, const Gemm g, const Sched S, const Epi E) {
;     ...
;             PG8_LDB(B0, 0, 0); PG8_LDB(B1, 0, 1); PG8_SCHED; PG8_LDA(At, 0, 0); PG8_STAGE(PG8_SA(1, 1), a1 + hstep, voffA);
;             PG8_WAIT_V(8); PG8_WAIT_L(0); PG8_BAR; PG8_MMA(0, 0, At, B0); PG8_MMA(0, 1, At, B1); PG8_BAR; PG8_SCHED;
;             PG8_LDA(At, 0, 1); PG8_STAGE(PG8_SB(0, 0), b2, voffB); PG8_STAGE(PG8_SB(0, 1), b2 + hstep, voffB); PG8_STAGE(PG8_SA(0, 0), a2, voffA);
;             PG8_WAIT_V(8); PG8_WAIT_L(0); PG8_BAR; PG8_MMA(1, 0, At, B0); PG8_MMA(1, 1, At, B1); PG8_BAR; PG8_SCHED;
.LBB0_538:
	v_add_u32_e32 v155, 0x10000, v152
	ds_read_b128 v[146:149], v155
	ds_read_b128 v[156:159], v155 offset:1024
	ds_read_b128 v[160:163], v155 offset:2048
	ds_read_b128 v[164:167], v155 offset:3072
	v_add_u32_e32 v155, 0x14000, v152
	ds_read_b128 v[168:171], v155
	ds_read_b128 v[172:175], v155 offset:1024
	ds_read_b128 v[182:185], v155 offset:2048
	ds_read_b128 v[198:201], v155 offset:3072
	s_add_i32 s3, s14, 2
	s_add_u32 s15, s68, s16
	s_addc_u32 s18, s69, s17
	s_add_u32 s20, s66, s16
	s_addc_u32 s21, s67, s17
	s_add_i32 s22, 0, 0x10000
	s_cmp_eq_u32 s81, s14
	s_cselect_b32 s19, s1, s18
	s_cselect_b32 s18, s0, s15
	s_cselect_b32 s15, s55, s21
	s_cselect_b32 s14, s54, s20
	s_add_i32 s20, 0, 0x14000
	v_lshl_add_u64 v[176:177], s[68:69], 0, v[144:145]
	s_add_i32 m0, s72, 0xc000
	ds_read_b128 v[202:205], v154
	ds_read_b128 v[206:209], v154 offset:1024
	ds_read_b128 v[210:213], v154 offset:2048
	ds_read_b128 v[214:217], v154 offset:3072
	ds_read_b128 v[218:221], v154 offset:4096
	ds_read_b128 v[222:225], v154 offset:5120
	ds_read_b128 v[226:229], v154 offset:6144
	ds_read_b128 v[230:233], v154 offset:7168
	global_load_lds_dwordx4 v[176:177], off
	v_lshl_add_u64 v[176:177], s[68:69], 0, v[142:143]
	s_add_i32 m0, s72, 0xe000
	s_nop 0
	global_load_lds_dwordx4 v[176:177], off
	s_waitcnt vmcnt(8) lgkmcnt(0)
	s_barrier
	s_setprio 1
	v_mfma_f32_16x16x32_bf16 v[62:65], v[146:149], v[202:205], v[62:65]
	v_mfma_f32_16x16x32_bf16 v[54:57], v[160:163], v[202:205], v[54:57]
	v_mfma_f32_16x16x32_bf16 v[14:17], v[146:149], v[210:213], v[14:17]
	v_mfma_f32_16x16x32_bf16 v[10:13], v[160:163], v[210:213], v[10:13]
	v_mfma_f32_16x16x32_bf16 v[30:33], v[146:149], v[218:221], v[30:33]
	v_mfma_f32_16x16x32_bf16 v[26:29], v[160:163], v[218:221], v[26:29]
	v_mfma_f32_16x16x32_bf16 v[46:49], v[146:149], v[226:229], v[46:49]
	v_mfma_f32_16x16x32_bf16 v[42:45], v[160:163], v[226:229], v[42:45]
	v_mfma_f32_16x16x32_bf16 v[62:65], v[156:159], v[206:209], v[62:65]
	v_mfma_f32_16x16x32_bf16 v[54:57], v[164:167], v[206:209], v[54:57]
	v_mfma_f32_16x16x32_bf16 v[14:17], v[156:159], v[214:217], v[14:17]
	v_mfma_f32_16x16x32_bf16 v[10:13], v[164:167], v[214:217], v[10:13]
	v_mfma_f32_16x16x32_bf16 v[30:33], v[156:159], v[222:225], v[30:33]
	v_mfma_f32_16x16x32_bf16 v[26:29], v[164:167], v[222:225], v[26:29]
	v_mfma_f32_16x16x32_bf16 v[46:49], v[156:159], v[230:233], v[46:49]
	v_mfma_f32_16x16x32_bf16 v[42:45], v[164:167], v[230:233], v[42:45]
	v_mfma_f32_16x16x32_bf16 v[6:9], v[168:171], v[202:205], v[6:9]
	v_mfma_f32_16x16x32_bf16 v[2:5], v[182:185], v[202:205], v[2:5]
	v_mfma_f32_16x16x32_bf16 v[22:25], v[168:171], v[210:213], v[22:25]
	v_mfma_f32_16x16x32_bf16 v[18:21], v[182:185], v[210:213], v[18:21]
	v_mfma_f32_16x16x32_bf16 v[38:41], v[168:171], v[218:221], v[38:41]
	v_mfma_f32_16x16x32_bf16 v[34:37], v[182:185], v[218:221], v[34:37]
	v_mfma_f32_16x16x32_bf16 v[58:61], v[168:171], v[226:229], v[58:61]
	v_mfma_f32_16x16x32_bf16 v[50:53], v[182:185], v[226:229], v[50:53]
	v_mfma_f32_16x16x32_bf16 v[6:9], v[172:175], v[206:209], v[6:9]
	v_mfma_f32_16x16x32_bf16 v[2:5], v[198:201], v[206:209], v[2:5]
	v_mfma_f32_16x16x32_bf16 v[22:25], v[172:175], v[214:217], v[22:25]
	v_mfma_f32_16x16x32_bf16 v[18:21], v[198:201], v[214:217], v[18:21]
	v_mfma_f32_16x16x32_bf16 v[38:41], v[172:175], v[222:225], v[38:41]
	v_mfma_f32_16x16x32_bf16 v[34:37], v[198:201], v[222:225], v[34:37]
	v_mfma_f32_16x16x32_bf16 v[58:61], v[172:175], v[230:233], v[58:61]
	v_mfma_f32_16x16x32_bf16 v[50:53], v[198:201], v[230:233], v[50:53]
	s_setprio 0
	s_barrier
	s_add_i32 s21, s22, s71
	v_lshl_add_u64 v[176:177], s[14:15], 0, v[0:1]
	s_mov_b32 m0, s21
	ds_read_b128 v[202:205], v154 offset:16384
	ds_read_b128 v[206:209], v154 offset:17408
	ds_read_b128 v[210:213], v154 offset:18432
	ds_read_b128 v[214:217], v154 offset:19456
	ds_read_b128 v[218:221], v154 offset:20480
	ds_read_b128 v[222:225], v154 offset:21504
	ds_read_b128 v[226:229], v154 offset:22528
	ds_read_b128 v[230:233], v154 offset:23552
	global_load_lds_dwordx4 v[176:177], off
	s_add_i32 m0, s21, 0x2000
	v_lshl_add_u64 v[234:235], s[14:15], 0, v[134:135]
	s_add_u32 s14, s14, s28
	s_addc_u32 s15, s15, 0
	s_add_i32 s20, s20, s71
	global_load_lds_dwordx4 v[234:235], off
	v_lshl_add_u64 v[236:237], s[14:15], 0, v[0:1]
	s_mov_b32 m0, s20
	v_lshl_add_u64 v[238:239], s[14:15], 0, v[134:135]
	global_load_lds_dwordx4 v[236:237], off
	s_add_i32 m0, s20, 0x2000
	v_lshl_add_u64 v[240:241], s[18:19], 0, v[130:131]
	global_load_lds_dwordx4 v[238:239], off
	s_mov_b32 m0, s72
	v_lshl_add_u64 v[242:243], s[18:19], 0, v[132:133]
	global_load_lds_dwordx4 v[240:241], off
	s_mov_b32 m0, s73
	s_nop 0
	global_load_lds_dwordx4 v[242:243], off
	s_waitcnt vmcnt(8) lgkmcnt(0)
	s_barrier
; #define PG8_STAGE(bufoff, gbase, voff) do { _Pragma("unroll") for (int _i = 0; _i < 2; ++_i) \
;         __builtin_amdgcn_global_load_lds((const unsigned*)((const char*)(gbase) + (voff)[_i]), (PG8_LAS unsigned*)(lds + (bufoff) + ldsw + _i * 8192), 16, 0, 0); } while (0)
; #define PG8_LDA(dst, b, h) do { _Pragma("unroll") for (int m = 0; m < 4; ++m) _Pragma("unroll") for (int k = 0; k < 2; ++k) dst[m][k] = *(const PG8_LAS bf16x8*)(lds + PG8_SA(b, h) + aoff + m * 2048 + k * 1024); } while (0)
; #define PG8_LDB(dst, b, h) do { _Pragma("unroll") for (int n = 0; n < 2; ++n) _Pragma("unroll") for (int k = 0; k < 2; ++k) dst[n][k] = *(const PG8_LAS bf16x8*)(lds + PG8_SB(b, h) + boff + n * 2048 + k * 1024); } while (0)
; #define PG8_MMA(ai, bj, At, Bt) do { __builtin_amdgcn_s_setprio(1); _Pragma("unroll") for (int m = 0; m < 4; ++m) _Pragma("unroll") for (int n = 0; n < 2; ++n) _Pragma("unroll") for (int k = 0; k < 2; ++k) \
;         acc[ai][bj][m][n] = __builtin_amdgcn_mfma_f32_16x16x32_bf16(Bt[n][k], At[m][k], acc[ai][bj][m][n], 0, 0, 0); __builtin_amdgcn_s_setprio(0); } while (0)
; #define PG8_WAIT_V(n) asm volatile("s_waitcnt vmcnt(" #n ")" ::: "memory")
; #define PG8_WAIT_L(n) asm volatile("s_waitcnt lgkmcnt(" #n ")" ::: "memory")
; #define PG8_BAR __builtin_amdgcn_s_barrier()
; #define PG8_SCHED __builtin_amdgcn_sched_barrier(0)
; template <class Epi, class Sched, bool ALIGN_EPI = false, bool SP2 = false>
; __device__ __forceinline__ void gemm_phase(PG8_LAS unsigned char* lds, const Gemm g, const Sched S, const Epi E) {
;     ...
;             PG8_WAIT_V(8); PG8_WAIT_L(0); PG8_BAR; PG8_MMA(1, 0, At, B0); PG8_MMA(1, 1, At, B1); PG8_BAR; PG8_SCHED;
;             PG8_LDB(B0, 1, 0); PG8_LDB(B1, 1, 1); PG8_SCHED; PG8_LDA(At, 1, 0); PG8_STAGE(PG8_SA(0, 1), a2 + hstep, voffA);
;             PG8_WAIT_V(8); PG8_WAIT_L(0); PG8_BAR; PG8_MMA(0, 0, At, B0); PG8_MMA(0, 1, At, B1); PG8_BAR; PG8_SCHED;
	s_setprio 1
	v_mfma_f32_16x16x32_bf16 v[70:73], v[146:149], v[202:205], v[70:73]
	v_mfma_f32_16x16x32_bf16 v[66:69], v[160:163], v[202:205], v[66:69]
	v_mfma_f32_16x16x32_bf16 v[86:89], v[146:149], v[210:213], v[86:89]
	v_mfma_f32_16x16x32_bf16 v[82:85], v[160:163], v[210:213], v[82:85]
	v_mfma_f32_16x16x32_bf16 v[102:105], v[146:149], v[218:221], v[102:105]
	v_mfma_f32_16x16x32_bf16 v[98:101], v[160:163], v[218:221], v[98:101]
	v_mfma_f32_16x16x32_bf16 v[118:121], v[146:149], v[226:229], v[118:121]
	v_mfma_f32_16x16x32_bf16 v[114:117], v[160:163], v[226:229], v[114:117]
	v_mfma_f32_16x16x32_bf16 v[70:73], v[156:159], v[206:209], v[70:73]
	v_mfma_f32_16x16x32_bf16 v[66:69], v[164:167], v[206:209], v[66:69]
	v_mfma_f32_16x16x32_bf16 v[86:89], v[156:159], v[214:217], v[86:89]
	v_mfma_f32_16x16x32_bf16 v[82:85], v[164:167], v[214:217], v[82:85]
	v_mfma_f32_16x16x32_bf16 v[102:105], v[156:159], v[222:225], v[102:105]
	v_mfma_f32_16x16x32_bf16 v[98:101], v[164:167], v[222:225], v[98:101]
	v_mfma_f32_16x16x32_bf16 v[118:121], v[156:159], v[230:233], v[118:121]
	v_mfma_f32_16x16x32_bf16 v[114:117], v[164:167], v[230:233], v[114:117]
	v_mfma_f32_16x16x32_bf16 v[78:81], v[168:171], v[202:205], v[78:81]
	v_mfma_f32_16x16x32_bf16 v[74:77], v[182:185], v[202:205], v[74:77]
	v_mfma_f32_16x16x32_bf16 v[94:97], v[168:171], v[210:213], v[94:97]
	v_mfma_f32_16x16x32_bf16 v[90:93], v[182:185], v[210:213], v[90:93]
	v_mfma_f32_16x16x32_bf16 v[110:113], v[168:171], v[218:221], v[110:113]
	v_mfma_f32_16x16x32_bf16 v[106:109], v[182:185], v[218:221], v[106:109]
	v_mfma_f32_16x16x32_bf16 v[126:129], v[168:171], v[226:229], v[126:129]
	v_mfma_f32_16x16x32_bf16 v[122:125], v[182:185], v[226:229], v[122:125]
	v_mfma_f32_16x16x32_bf16 v[78:81], v[172:175], v[206:209], v[78:81]
	v_mfma_f32_16x16x32_bf16 v[74:77], v[198:201], v[206:209], v[74:77]
	v_mfma_f32_16x16x32_bf16 v[94:97], v[172:175], v[214:217], v[94:97]
	v_mfma_f32_16x16x32_bf16 v[90:93], v[198:201], v[214:217], v[90:93]
	v_mfma_f32_16x16x32_bf16 v[110:113], v[172:175], v[222:225], v[110:113]
	v_mfma_f32_16x16x32_bf16 v[106:109], v[198:201], v[222:225], v[106:109]
	v_mfma_f32_16x16x32_bf16 v[126:129], v[172:175], v[230:233], v[126:129]
	v_mfma_f32_16x16x32_bf16 v[122:125], v[198:201], v[230:233], v[122:125]
	s_setprio 0
	s_barrier
	v_add_u32_e32 v155, 0x18000, v152
	ds_read_b128 v[146:149], v155
	ds_read_b128 v[156:159], v155 offset:1024
	ds_read_b128 v[160:163], v155 offset:2048
	ds_read_b128 v[164:167], v155 offset:3072
	v_add_u32_e32 v155, 0x1c000, v152
	ds_read_b128 v[168:171], v155
	ds_read_b128 v[172:175], v155 offset:1024
	ds_read_b128 v[182:185], v155 offset:2048
	ds_read_b128 v[198:201], v155 offset:3072
	s_add_i32 s20, 0, 0x18000
	s_add_i32 s21, 0, 0x1c000
	s_add_u32 s14, s18, s28
	s_addc_u32 s15, s19, 0
	s_mov_b32 m0, s74
	v_lshl_add_u64 v[244:245], s[14:15], 0, v[130:131]
	ds_read_b128 v[202:205], v154 offset:32768
	ds_read_b128 v[206:209], v154 offset:33792
	ds_read_b128 v[210:213], v154 offset:34816
	ds_read_b128 v[214:217], v154 offset:35840
	ds_read_b128 v[218:221], v154 offset:36864
	ds_read_b128 v[222:225], v154 offset:37888
	ds_read_b128 v[226:229], v154 offset:38912
	ds_read_b128 v[230:233], v154 offset:39936
	global_load_lds_dwordx4 v[244:245], off
	v_lshl_add_u64 v[244:245], s[14:15], 0, v[132:133]
	s_mov_b32 m0, s75
	s_nop 0
	global_load_lds_dwordx4 v[244:245], off
	s_waitcnt vmcnt(8) lgkmcnt(0)
	s_barrier
	s_setprio 1
	v_mfma_f32_16x16x32_bf16 v[62:65], v[146:149], v[202:205], v[62:65]
	v_mfma_f32_16x16x32_bf16 v[54:57], v[160:163], v[202:205], v[54:57]
	v_mfma_f32_16x16x32_bf16 v[14:17], v[146:149], v[210:213], v[14:17]
	v_mfma_f32_16x16x32_bf16 v[10:13], v[160:163], v[210:213], v[10:13]
	v_mfma_f32_16x16x32_bf16 v[30:33], v[146:149], v[218:221], v[30:33]
	v_mfma_f32_16x16x32_bf16 v[26:29], v[160:163], v[218:221], v[26:29]
	v_mfma_f32_16x16x32_bf16 v[46:49], v[146:149], v[226:229], v[46:49]
	v_mfma_f32_16x16x32_bf16 v[42:45], v[160:163], v[226:229], v[42:45]
	v_mfma_f32_16x16x32_bf16 v[62:65], v[156:159], v[206:209], v[62:65]
	v_mfma_f32_16x16x32_bf16 v[54:57], v[164:167], v[206:209], v[54:57]
	v_mfma_f32_16x16x32_bf16 v[14:17], v[156:159], v[214:217], v[14:17]
	v_mfma_f32_16x16x32_bf16 v[10:13], v[164:167], v[214:217], v[10:13]
	v_mfma_f32_16x16x32_bf16 v[30:33], v[156:159], v[222:225], v[30:33]
	v_mfma_f32_16x16x32_bf16 v[26:29], v[164:167], v[222:225], v[26:29]
	v_mfma_f32_16x16x32_bf16 v[46:49], v[156:159], v[230:233], v[46:49]
	v_mfma_f32_16x16x32_bf16 v[42:45], v[164:167], v[230:233], v[42:45]
	v_mfma_f32_16x16x32_bf16 v[6:9], v[168:171], v[202:205], v[6:9]
	v_mfma_f32_16x16x32_bf16 v[2:5], v[182:185], v[202:205], v[2:5]
	v_mfma_f32_16x16x32_bf16 v[22:25], v[168:171], v[210:213], v[22:25]
	v_mfma_f32_16x16x32_bf16 v[18:21], v[182:185], v[210:213], v[18:21]
	v_mfma_f32_16x16x32_bf16 v[38:41], v[168:171], v[218:221], v[38:41]
	v_mfma_f32_16x16x32_bf16 v[34:37], v[182:185], v[218:221], v[34:37]
	v_mfma_f32_16x16x32_bf16 v[58:61], v[168:171], v[226:229], v[58:61]
	v_mfma_f32_16x16x32_bf16 v[50:53], v[182:185], v[226:229], v[50:53]
	v_mfma_f32_16x16x32_bf16 v[6:9], v[172:175], v[206:209], v[6:9]
	v_mfma_f32_16x16x32_bf16 v[2:5], v[198:201], v[206:209], v[2:5]
	v_mfma_f32_16x16x32_bf16 v[22:25], v[172:175], v[214:217], v[22:25]
	v_mfma_f32_16x16x32_bf16 v[18:21], v[198:201], v[214:217], v[18:21]
	v_mfma_f32_16x16x32_bf16 v[38:41], v[172:175], v[222:225], v[38:41]
	v_mfma_f32_16x16x32_bf16 v[34:37], v[198:201], v[222:225], v[34:37]
	v_mfma_f32_16x16x32_bf16 v[58:61], v[172:175], v[230:233], v[58:61]
	v_mfma_f32_16x16x32_bf16 v[50:53], v[198:201], v[230:233], v[50:53]
	s_setprio 0
	s_barrier
; #define PG8_STAGE(bufoff, gbase, voff) do { _Pragma("unroll") for (int _i = 0; _i < 2; ++_i) \
;         __builtin_amdgcn_global_load_lds((const unsigned*)((const char*)(gbase) + (voff)[_i]), (PG8_LAS unsigned*)(lds + (bufoff) + ldsw + _i * 8192), 16, 0, 0); } while (0)
; #define PG8_LDA(dst, b, h) do { _Pragma("unroll") for (int m = 0; m < 4; ++m) _Pragma("unroll") for (int k = 0; k < 2; ++k) dst[m][k] = *(const PG8_LAS bf16x8*)(lds + PG8_SA(b, h) + aoff + m * 2048 + k * 1024); } while (0)
; #define PG8_MMA(ai, bj, At, Bt) do { __builtin_amdgcn_s_setprio(1); _Pragma("unroll") for (int m = 0; m < 4; ++m) _Pragma("unroll") for (int n = 0; n < 2; ++n) _Pragma("unroll") for (int k = 0; k < 2; ++k) \
;         acc[ai][bj][m][n] = __builtin_amdgcn_mfma_f32_16x16x32_bf16(Bt[n][k], At[m][k], acc[ai][bj][m][n], 0, 0, 0); __builtin_amdgcn_s_setprio(0); } while (0)
; #define PG8_WAIT_V(n) asm volatile("s_waitcnt vmcnt(" #n ")" ::: "memory")
; #define PG8_WAIT_L(n) asm volatile("s_waitcnt lgkmcnt(" #n ")" ::: "memory")
; #define PG8_BAR __builtin_amdgcn_s_barrier()
; #define PG8_SCHED __builtin_amdgcn_sched_barrier(0)
; template <class Epi, class Sched, bool ALIGN_EPI = false, bool SP2 = false>
; __device__ __forceinline__ void gemm_phase(PG8_LAS unsigned char* lds, const Gemm g, const Sched S, const Epi E) {
;     ...
;             PG8_LDA(At, 1, 1); PG8_STAGE(PG8_SB(1, 0), b3, voffB); PG8_STAGE(PG8_SB(1, 1), b3 + hstep, voffB); PG8_STAGE(PG8_SA(1, 0), a3, voffA);
;             PG8_WAIT_V(8); PG8_WAIT_L(0); PG8_BAR; PG8_MMA(1, 0, At, B0); PG8_MMA(1, 1, At, B1); PG8_BAR; PG8_SCHED;
	s_add_i32 s14, s20, s71
	v_lshl_add_u64 v[176:177], v[176:177], 0, s[12:13]
	s_mov_b32 m0, s14
	ds_read_b128 v[202:205], v154 offset:49152
	ds_read_b128 v[206:209], v154 offset:50176
	ds_read_b128 v[210:213], v154 offset:51200
	ds_read_b128 v[214:217], v154 offset:52224
	ds_read_b128 v[218:221], v154 offset:53248
	ds_read_b128 v[222:225], v154 offset:54272
	ds_read_b128 v[226:229], v154 offset:55296
	ds_read_b128 v[230:233], v154 offset:56320
	global_load_lds_dwordx4 v[176:177], off
	v_lshl_add_u64 v[176:177], v[234:235], 0, s[12:13]
	s_add_i32 m0, s14, 0x2000
	s_add_i32 s14, s21, s71
	global_load_lds_dwordx4 v[176:177], off
	v_lshl_add_u64 v[176:177], v[236:237], 0, s[12:13]
	s_mov_b32 m0, s14
	s_nop 0
	global_load_lds_dwordx4 v[176:177], off
	v_lshl_add_u64 v[176:177], v[238:239], 0, s[12:13]
	s_add_i32 m0, s14, 0x2000
	s_nop 0
	global_load_lds_dwordx4 v[176:177], off
	v_lshl_add_u64 v[176:177], v[240:241], 0, s[12:13]
	s_mov_b32 m0, s77
	s_nop 0
	global_load_lds_dwordx4 v[176:177], off
	v_lshl_add_u64 v[176:177], v[242:243], 0, s[12:13]
	s_mov_b32 m0, s78
	s_nop 0
	global_load_lds_dwordx4 v[176:177], off
	s_waitcnt vmcnt(8) lgkmcnt(0)
	s_barrier
	s_setprio 1
	v_mfma_f32_16x16x32_bf16 v[70:73], v[146:149], v[202:205], v[70:73]
	v_mfma_f32_16x16x32_bf16 v[66:69], v[160:163], v[202:205], v[66:69]
	v_mfma_f32_16x16x32_bf16 v[86:89], v[146:149], v[210:213], v[86:89]
	v_mfma_f32_16x16x32_bf16 v[82:85], v[160:163], v[210:213], v[82:85]
	v_mfma_f32_16x16x32_bf16 v[102:105], v[146:149], v[218:221], v[102:105]
	v_mfma_f32_16x16x32_bf16 v[98:101], v[160:163], v[218:221], v[98:101]
	v_mfma_f32_16x16x32_bf16 v[118:121], v[146:149], v[226:229], v[118:121]
	v_mfma_f32_16x16x32_bf16 v[114:117], v[160:163], v[226:229], v[114:117]
	v_mfma_f32_16x16x32_bf16 v[70:73], v[156:159], v[206:209], v[70:73]
	v_mfma_f32_16x16x32_bf16 v[66:69], v[164:167], v[206:209], v[66:69]
	v_mfma_f32_16x16x32_bf16 v[86:89], v[156:159], v[214:217], v[86:89]
	v_mfma_f32_16x16x32_bf16 v[82:85], v[164:167], v[214:217], v[82:85]
	v_mfma_f32_16x16x32_bf16 v[102:105], v[156:159], v[222:225], v[102:105]
	v_mfma_f32_16x16x32_bf16 v[98:101], v[164:167], v[222:225], v[98:101]
	v_mfma_f32_16x16x32_bf16 v[118:121], v[156:159], v[230:233], v[118:121]
	v_mfma_f32_16x16x32_bf16 v[114:117], v[164:167], v[230:233], v[114:117]
	v_mfma_f32_16x16x32_bf16 v[78:81], v[168:171], v[202:205], v[78:81]
	v_mfma_f32_16x16x32_bf16 v[74:77], v[182:185], v[202:205], v[74:77]
	v_mfma_f32_16x16x32_bf16 v[94:97], v[168:171], v[210:213], v[94:97]
	v_mfma_f32_16x16x32_bf16 v[90:93], v[182:185], v[210:213], v[90:93]
	v_mfma_f32_16x16x32_bf16 v[110:113], v[168:171], v[218:221], v[110:113]
	v_mfma_f32_16x16x32_bf16 v[106:109], v[182:185], v[218:221], v[106:109]
	v_mfma_f32_16x16x32_bf16 v[126:129], v[168:171], v[226:229], v[126:129]
	v_mfma_f32_16x16x32_bf16 v[122:125], v[182:185], v[226:229], v[122:125]
	v_mfma_f32_16x16x32_bf16 v[78:81], v[172:175], v[206:209], v[78:81]
	v_mfma_f32_16x16x32_bf16 v[74:77], v[198:201], v[206:209], v[74:77]
	v_mfma_f32_16x16x32_bf16 v[94:97], v[172:175], v[214:217], v[94:97]
	v_mfma_f32_16x16x32_bf16 v[90:93], v[198:201], v[214:217], v[90:93]
	v_mfma_f32_16x16x32_bf16 v[110:113], v[172:175], v[222:225], v[110:113]
	v_mfma_f32_16x16x32_bf16 v[106:109], v[198:201], v[222:225], v[106:109]
	v_mfma_f32_16x16x32_bf16 v[126:129], v[172:175], v[230:233], v[126:129]
	v_mfma_f32_16x16x32_bf16 v[122:125], v[198:201], v[230:233], v[122:125]
	s_setprio 0
	s_add_u32 s16, s16, 0x100
	s_addc_u32 s17, s17, 0
	v_lshl_add_u64 v[144:145], v[144:145], 0, s[88:89]
	v_lshl_add_u64 v[142:143], v[142:143], 0, s[88:89]
	s_cmp_ge_u32 s3, s76
	s_mov_b32 s14, s3
	s_barrier
	s_cbranch_scc0 .LBB0_538
	s_and_b64 vcc, exec, s[62:63]
	s_cbranch_vccz .LBB0_541
	s_barrier
